# sample attention loops: wave 0 (the only computing wave) raises its priority (s_setprio 2) during its per-tile compute, back to 0 at the join
# baseline (speedup 1.0000x reference)
; template <int MODE, bool SAMPLE>
; __device__ __forceinline__ void attn_unit(const Params& p, char* lds, int b, int h, int qb) {
;     ...
; #pragma unroll
;     ...
;         const int j = 2 * jj + par;
;         if (j > jfirst) continue;
;         const int buf = par;
;         WRITET(buf, stg2[NS == 2 ? par : 0]);
;         if (j >= NS) LOADT(j - NS, stg2[NS == 2 ? par : 0]);
;         __syncthreads();
;         if (wact && j <= jd && var < 2) {
;             const char* Kt = K_lds + buf * 16384; const int vb = vb0 + buf * 16384;
;             f32x16 p0, p1; bf16x8 pa0, pa1, pa2, pa3;
;             if (MODE == 0) {
;                 const float* bt = biasL + j * 64 + 4 * hi;
; #pragma unroll
;                 for (int g = 0; g < 4; ++g) { const f32x4 a = *(const f32x4*)(bt + 8 * g), c = *(const f32x4*)(bt + 32 + 8 * g);
; #pragma unroll
;                     for (int i = 0; i < 4; ++i) { p0[4 * g + i] = a[i]; p1[4 * g + i] = c[i]; } }
;                 qkt(p0, p1, Kt, Qs, r32, hi);
.LBB0_614:
	s_setprio 0
	s_mov_b32 s0, 0xfffe0000
	s_add_i32 s76, s76, -1
	s_addk_i32 s54, 0xff80
	s_addk_i32 s97, 0xfe00
	s_mov_b32 s1, -1
	s_cmpk_eq_i32 s97, 0xee00
	v_lshl_add_u64 v[170:171], v[170:171], 0, s[0:1]
	s_cbranch_scc1 .LBB0_630
.LBB0_615:
	v_cndmask_b32_e64 v66, 0, 1, s[74:75]
	s_cmp_lt_u32 s76, 8
	v_lshlrev_b32_e32 v0, 2, v152
	v_lshlrev_b32_e32 v164, 2, v154
	v_cmp_ne_u32_e64 s[0:1], 1, v66
	s_cbranch_scc0 .Lfsr_first_f1
	v_and_b32_e32 v76, 15, v183
	v_bfe_u32 v77, v183, 4, 3
	v_xor_b32_e32 v78, v76, v77
	v_lshrrev_b32_e32 v74, 1, v76
	v_xor_b32_e32 v74, v74, v77
	v_sub_u32_e32 v74, v74, v78
	v_and_b32_e32 v78, 1, v76
	v_lshlrev_b32_e32 v74, 4, v74
	v_lshl_add_u32 v74, v78, 3, v74
	v_lshrrev_b32_e32 v75, 3, v76
	v_lshrrev_b32_e32 v78, 2, v76
	v_sub_u32_e32 v75, v75, v78
	v_lshlrev_b32_e32 v75, 9, v75
	v_and_b32_e32 v78, 7, v76
	v_lshl_add_u32 v75, v78, 3, v75
	v_and_b32_e32 v78, 3, v76
	v_lshlrev_b32_e32 v78, 4, v78
	v_sub_u32_e32 v75, v75, v78
	v_add_u32_e32 v70, v133, v74
	v_add_u32_e32 v71, v198, v74
	v_add_u32_e32 v72, v199, v75
	v_add_u32_e32 v73, v200, v75
	s_waitcnt vmcnt(6)
	v_cvt_pk_bf16_f32 v66, v102, v103
	v_cvt_pk_bf16_f32 v67, v104, v105
	v_cvt_pk_bf16_f32 v68, v98, v99
	v_cvt_pk_bf16_f32 v69, v100, v101
	ds_write_b64 v70, v[66:67] offset:16384
	ds_write_b64 v70, v[68:69] offset:16512
	s_waitcnt vmcnt(4)
	v_cvt_pk_bf16_f32 v66, v110, v111
	v_cvt_pk_bf16_f32 v67, v112, v113
	v_cvt_pk_bf16_f32 v68, v106, v107
	v_cvt_pk_bf16_f32 v69, v108, v109
	ds_write_b64 v71, v[66:67] offset:16384
	ds_write_b64 v71, v[68:69] offset:16512
	s_waitcnt vmcnt(2)
	v_cvt_pk_bf16_f32 v66, v122, v123
	v_cvt_pk_bf16_f32 v67, v124, v125
	v_cvt_pk_bf16_f32 v68, v114, v115
	v_cvt_pk_bf16_f32 v69, v116, v117
	ds_write_b64 v72, v[66:67] offset:49152
	ds_write_b64 v72, v[68:69] offset:50176
	s_waitcnt vmcnt(0)
	v_cvt_pk_bf16_f32 v66, v126, v127
	v_cvt_pk_bf16_f32 v67, v128, v129
	v_cvt_pk_bf16_f32 v68, v118, v119
	v_cvt_pk_bf16_f32 v69, v120, v121
	ds_write_b64 v73, v[66:67] offset:49152
	ds_write_b64 v73, v[68:69] offset:50176
	v_or_b32_e32 v67, s11, v171
	v_or_b32_e32 v66, s3, v170
	v_readlane_b32 s36, v253, 16
	v_lshlrev_b64 v[66:67], 2, v[66:67]
	v_and_b32_e32 v72, 15, v183
	v_lshlrev_b32_e32 v72, 4, v72
	v_sub_u32_e32 v66, v66, v72
	v_readlane_b32 s40, v253, 20
	v_readlane_b32 s41, v253, 21
	v_readlane_b32 s42, v253, 22
	v_readlane_b32 s43, v253, 23
	v_lshl_add_u64 v[68:69], s[40:41], 0, v[66:67]
	v_mov_b32_e32 v165, v1
	v_lshl_add_u64 v[70:71], v[68:69], 0, v[0:1]
	v_lshl_add_u64 v[68:69], v[68:69], 0, v[164:165]
	v_lshl_add_u64 v[66:67], s[42:43], 0, v[66:67]
	global_load_dwordx4 v[98:101], v[70:71], off offset:256 nt
	global_load_dwordx4 v[102:105], v[70:71], off nt
	global_load_dwordx4 v[106:109], v[68:69], off offset:256 nt
	global_load_dwordx4 v[110:113], v[68:69], off nt
	v_lshl_add_u64 v[68:69], v[66:67], 0, v[0:1]
	v_lshl_add_u64 v[66:67], v[66:67], 0, v[164:165]
	global_load_dwordx4 v[114:117], v[68:69], off offset:256 nt
	global_load_dwordx4 v[122:125], v[68:69], off nt
	global_load_dwordx4 v[118:121], v[66:67], off offset:256 nt
	global_load_dwordx4 v[126:129], v[66:67], off nt
	s_and_b64 vcc, exec, s[0:1]
	v_readlane_b32 s37, v253, 17
	v_readlane_b32 s38, v253, 18
	v_readlane_b32 s39, v253, 19
	v_readlane_b32 s44, v253, 24
	v_readlane_b32 s45, v253, 25
	v_readlane_b32 s46, v253, 26
	v_readlane_b32 s47, v253, 27
	v_readlane_b32 s48, v253, 28
	v_readlane_b32 s49, v253, 29
	v_readlane_b32 s50, v253, 30
	v_readlane_b32 s51, v253, 31
	s_waitcnt lgkmcnt(0)
	s_barrier
	s_cbranch_vccnz .LBB0_622
	s_setprio 2
	v_add_u32_e32 v78, s97, v214
	v_add_u32_e32 v66, 0x11100, v78
	v_add_u32_e32 v67, 0x11180, v78
	v_add_u32_e32 v70, 0x11120, v78
	v_add_u32_e32 v74, 0x11140, v78
	ds_read_b128 v[82:85], v66
	ds_read_b128 v[66:69], v67
	ds_read_b128 v[86:89], v70
	ds_read_b128 v[90:93], v74
	v_add_u32_e32 v70, 0x111a0, v78
	v_add_u32_e32 v74, 0x111c0, v78
	v_add_u32_e32 v79, 0x11160, v78
	v_add_u32_e32 v78, 0x111e0, v78
	ds_read_b128 v[94:97], v79
	ds_read_b128 v[78:81], v78
	ds_read_b128 v[70:73], v70
	ds_read_b128 v[74:77], v74
	v_add_u32_e32 v165, s33, v182
	ds_read_b128 v[202:205], v165
	ds_read_b128 v[206:209], v182 offset:16384
	ds_read_b128 v[216:219], v182 offset:24576
	v_add_u32_e32 v165, s33, v184
	ds_read_b128 v[234:237], v165
	ds_read_b128 v[238:241], v184 offset:16384
	ds_read_b128 v[242:245], v184 offset:24576
	s_waitcnt lgkmcnt(4)
	v_mfma_f32_32x32x16_bf16 v[82:97], v[206:209], v[202:205], v[82:97]
	s_waitcnt lgkmcnt(3)
	v_mfma_f32_32x32x16_bf16 v[66:81], v[216:219], v[202:205], v[66:81]
	v_add_u32_e32 v165, s33, v185
	ds_read_b128 v[202:205], v165
	ds_read_b128 v[206:209], v185 offset:16384
	ds_read_b128 v[216:219], v185 offset:24576
	s_waitcnt lgkmcnt(4)
	v_mfma_f32_32x32x16_bf16 v[82:97], v[238:241], v[234:237], v[82:97]
	s_waitcnt lgkmcnt(3)
	v_mfma_f32_32x32x16_bf16 v[66:81], v[242:245], v[234:237], v[66:81]
	v_add_u32_e32 v165, s33, v186
	ds_read_b128 v[234:237], v165
	ds_read_b128 v[238:241], v186 offset:16384
	ds_read_b128 v[242:245], v186 offset:24576
	s_waitcnt lgkmcnt(4)
	v_mfma_f32_32x32x16_bf16 v[82:97], v[206:209], v[202:205], v[82:97]
	s_waitcnt lgkmcnt(3)
	v_mfma_f32_32x32x16_bf16 v[66:81], v[216:219], v[202:205], v[66:81]
	v_add_u32_e32 v165, s33, v187
	ds_read_b128 v[202:205], v165
	ds_read_b128 v[206:209], v187 offset:16384
	ds_read_b128 v[216:219], v187 offset:24576
	s_waitcnt lgkmcnt(4)
	v_mfma_f32_32x32x16_bf16 v[82:97], v[238:241], v[234:237], v[82:97]
	s_waitcnt lgkmcnt(3)
	v_mfma_f32_32x32x16_bf16 v[66:81], v[242:245], v[234:237], v[66:81]
	v_add_u32_e32 v165, s33, v188
	ds_read_b128 v[234:237], v165
	ds_read_b128 v[238:241], v188 offset:16384
	ds_read_b128 v[242:245], v188 offset:24576
	s_waitcnt lgkmcnt(4)
; __device__ __forceinline__ int crow(int r, int hi) { return (r & 3) + 8 * (r >> 2) + 4 * hi; }
; __device__ __forceinline__ void qkt(f32x16& p0, f32x16& p1, const char* Ks, const char* Qs, int r32, int hi) {
; #pragma unroll
;     for (int d0 = 0; d0 < 8; ++d0) { const int cb = (d0 * 16 + hi * 8) * 2;
;         const bf16x8 qv = *reinterpret_cast<const bf16x8*>(Qs + KSWZ(r32, cb));
;         const bf16x8 b0 = *reinterpret_cast<const bf16x8*>(Ks + KSWZ(r32, cb));
;         const bf16x8 b1 = *reinterpret_cast<const bf16x8*>(Ks + KSWZ(32 + r32, cb));
;         p0 = __builtin_amdgcn_mfma_f32_32x32x16_bf16(b0, qv, p0, 0, 0, 0);
;         p1 = __builtin_amdgcn_mfma_f32_32x32x16_bf16(b1, qv, p1, 0, 0, 0); }
; }
; template <int MODE, bool SAMPLE>
; __device__ __forceinline__ void attn_unit(const Params& p, char* lds, int b, int h, int qb) {
;     ...
;                 float pmax = p0[0];
; #pragma unroll
;                 for (int r = 1; r < 16; ++r) pmax = fmaxf(pmax, p0[r]);
; #pragma unroll
;                 for (int r = 0; r < 16; ++r) pmax = fmaxf(pmax, p1[r]);
;                 { auto rr = __builtin_amdgcn_permlane32_swap(__float_as_uint(pmax), __float_as_uint(pmax), false, false); pmax = fmaxf(__uint_as_float(rr[0]), __uint_as_float(rr[1])); }
;                 float alpha = 1.f;
;                 if (!__all(pmax - m_reg <= 8.f)) { const float mn = fmaxf(m_reg, pmax); alpha = __builtin_amdgcn_exp2f(m_reg - mn); m_reg = mn; }
;                 float ps = 0.f;
; #pragma unroll
;                 for (int r = 0; r < 16; ++r) { p0[r] = __builtin_amdgcn_exp2f(p0[r] - m_reg); p1[r] = __builtin_amdgcn_exp2f(p1[r] - m_reg); ps += p0[r] + p1[r]; }
;                 { auto rr = __builtin_amdgcn_permlane32_swap(__float_as_uint(ps), __float_as_uint(ps), false, false); ps = __uint_as_float(rr[0]) + __uint_as_float(rr[1]); }
;                 l_reg = l_reg * alpha + ps;
;                 if (__any(alpha < 1.f)) { if (hi == 0) wsc[r32] = alpha; asm volatile("s_waitcnt lgkmcnt(0)" ::: "memory");
; #pragma unroll
;                     for (int d = 0; d < 4; ++d)
; #pragma unroll
;                         for (int r = 0; r < 16; ++r) o[d][r] *= wsc[crow(r, hi)]; }
	v_mfma_f32_32x32x16_bf16 v[82:97], v[206:209], v[202:205], v[82:97]
	s_waitcnt lgkmcnt(3)
	v_mfma_f32_32x32x16_bf16 v[66:81], v[216:219], v[202:205], v[66:81]
	v_add_u32_e32 v165, s33, v189
	ds_read_b128 v[202:205], v165
	ds_read_b128 v[206:209], v189 offset:16384
	ds_read_b128 v[216:219], v189 offset:24576
	s_waitcnt lgkmcnt(4)
	v_mfma_f32_32x32x16_bf16 v[82:97], v[238:241], v[234:237], v[82:97]
	s_waitcnt lgkmcnt(3)
	v_mfma_f32_32x32x16_bf16 v[66:81], v[242:245], v[234:237], v[66:81]
	v_add_u32_e32 v165, s33, v190
	ds_read_b128 v[234:237], v165
	ds_read_b128 v[238:241], v190 offset:16384
	ds_read_b128 v[242:245], v190 offset:24576
	s_waitcnt lgkmcnt(4)
	v_mfma_f32_32x32x16_bf16 v[82:97], v[206:209], v[202:205], v[82:97]
	s_waitcnt lgkmcnt(3)
	v_mfma_f32_32x32x16_bf16 v[66:81], v[216:219], v[202:205], v[66:81]
	s_waitcnt lgkmcnt(1)
	v_mfma_f32_32x32x16_bf16 v[82:97], v[238:241], v[234:237], v[82:97]
	s_waitcnt lgkmcnt(0)
	v_mfma_f32_32x32x16_bf16 v[66:81], v[242:245], v[234:237], v[66:81]
	s_nop 1
	s_nop 9
	v_max_f32_e32 v165, v83, v83
	v_max_f32_e32 v202, v82, v82
	v_max_f32_e32 v165, v202, v165
	v_max3_f32 v165, v165, v84, v85
	v_max3_f32 v165, v165, v86, v87
	v_max3_f32 v165, v165, v88, v89
	v_max3_f32 v165, v165, v90, v91
	v_max3_f32 v165, v165, v92, v93
	v_max3_f32 v165, v165, v94, v95
	v_max3_f32 v165, v165, v96, v97
	v_max3_f32 v165, v165, v66, v67
	v_max3_f32 v165, v165, v68, v69
	v_max3_f32 v165, v165, v70, v71
	v_max3_f32 v165, v165, v72, v73
	v_max3_f32 v165, v165, v74, v75
	v_max3_f32 v165, v165, v76, v77
	v_max3_f32 v165, v165, v78, v79
	v_max3_f32 v165, v165, v80, v81
	v_mov_b32_e32 v202, v165
	s_nop 1
	v_permlane32_swap_b32_e32 v165, v202
	v_max_f32_e32 v202, v202, v202
	v_max_f32_e32 v165, v165, v165
	v_max_f32_e32 v165, v165, v202
	v_sub_f32_e32 v202, v165, v163
	v_cmp_ge_f32_e32 vcc, s83, v202
	s_cmp_eq_u64 vcc, exec
	v_max_f32_e32 v202, v163, v163
	s_cselect_b64 vcc, -1, 0
	v_max_f32_e32 v165, v202, v165
	v_sub_f32_e32 v202, v163, v165
	v_cndmask_b32_e32 v163, v165, v163, vcc
	v_sub_f32_e32 v82, v82, v163
	v_sub_f32_e32 v66, v66, v163
	v_exp_f32_e32 v165, v82
	v_exp_f32_e32 v82, v66
	v_exp_f32_e32 v203, v202
	v_sub_f32_e32 v67, v67, v163
	v_sub_f32_e32 v68, v68, v163
	v_add_f32_e32 v66, v165, v82
	v_add_f32_e32 v202, 0, v66
	v_sub_f32_e32 v66, v83, v163
	v_exp_f32_e32 v66, v66
	v_exp_f32_e32 v83, v67
	v_sub_f32_e32 v69, v69, v163
	v_sub_f32_e32 v70, v70, v163
	v_exp_f32_e32 v70, v70
	v_add_f32_e32 v67, v66, v83
	v_add_f32_e32 v202, v67, v202
	v_sub_f32_e32 v67, v84, v163
	v_exp_f32_e32 v67, v67
	v_exp_f32_e32 v84, v68
	v_sub_f32_e32 v71, v71, v163
	v_exp_f32_e32 v71, v71
	v_sub_f32_e32 v72, v72, v163
	v_add_f32_e32 v68, v67, v84
	v_add_f32_e32 v202, v68, v202
	v_sub_f32_e32 v68, v85, v163
	v_exp_f32_e32 v68, v68
	v_exp_f32_e32 v85, v69
	v_exp_f32_e32 v72, v72
	v_sub_f32_e32 v73, v73, v163
	v_exp_f32_e32 v73, v73
	v_add_f32_e32 v69, v68, v85
	v_add_f32_e32 v202, v69, v202
	v_sub_f32_e32 v69, v86, v163
	v_exp_f32_e32 v69, v69
	v_sub_f32_e32 v74, v74, v163
	v_exp_f32_e32 v74, v74
	v_sub_f32_e32 v75, v75, v163
	v_add_f32_e32 v86, v69, v70
	v_add_f32_e32 v202, v86, v202
	v_sub_f32_e32 v86, v87, v163
	v_exp_f32_e32 v86, v86
	v_exp_f32_e32 v75, v75
	v_sub_f32_e32 v76, v76, v163
	v_exp_f32_e32 v76, v76
	v_add_f32_e32 v87, v86, v71
	v_add_f32_e32 v202, v87, v202
	v_sub_f32_e32 v87, v88, v163
	v_exp_f32_e32 v87, v87
	v_sub_f32_e32 v77, v77, v163
	v_exp_f32_e32 v77, v77
	v_sub_f32_e32 v78, v78, v163
	v_add_f32_e32 v88, v87, v72
	v_add_f32_e32 v202, v88, v202
	v_sub_f32_e32 v88, v89, v163
	v_exp_f32_e32 v88, v88
	v_exp_f32_e32 v78, v78
	v_sub_f32_e32 v79, v79, v163
	v_exp_f32_e32 v79, v79
	v_add_f32_e32 v89, v88, v73
	v_add_f32_e32 v202, v89, v202
	v_sub_f32_e32 v89, v90, v163
	v_exp_f32_e32 v89, v89
	v_sub_f32_e32 v80, v80, v163
	v_exp_f32_e32 v80, v80
	v_sub_f32_e32 v81, v81, v163
	v_add_f32_e32 v90, v89, v74
	v_add_f32_e32 v202, v90, v202
	v_sub_f32_e32 v90, v91, v163
	v_exp_f32_e32 v90, v90
	v_exp_f32_e32 v81, v81
	v_add_f32_e32 v91, v90, v75
	v_add_f32_e32 v202, v91, v202
	v_sub_f32_e32 v91, v92, v163
	v_exp_f32_e32 v91, v91
	s_nop 0
	v_add_f32_e32 v92, v91, v76
	v_add_f32_e32 v202, v92, v202
	v_sub_f32_e32 v92, v93, v163
	v_exp_f32_e32 v92, v92
	s_nop 0
	v_add_f32_e32 v93, v92, v77
	v_add_f32_e32 v202, v93, v202
	v_sub_f32_e32 v93, v94, v163
	v_exp_f32_e32 v93, v93
	s_nop 0
	v_add_f32_e32 v94, v93, v78
	v_add_f32_e32 v202, v94, v202
	v_sub_f32_e32 v94, v95, v163
	v_exp_f32_e32 v94, v94
	s_nop 0
	v_add_f32_e32 v95, v94, v79
	v_add_f32_e32 v202, v95, v202
	v_sub_f32_e32 v95, v96, v163
	v_exp_f32_e32 v95, v95
	s_nop 0
	v_add_f32_e32 v96, v95, v80
	v_add_f32_e32 v202, v96, v202
	v_sub_f32_e32 v96, v97, v163
	v_exp_f32_e32 v96, v96
	s_nop 0
	v_add_f32_e32 v97, v96, v81
	v_add_f32_e32 v202, v97, v202
	v_cndmask_b32_e64 v97, v203, 1.0, vcc
	v_mov_b32_e32 v203, v202
	s_nop 1
	v_permlane32_swap_b32_e32 v202, v203
	v_cmp_gt_f32_e32 vcc, 1.0, v97
	s_cbranch_vccz .LBB0_621
	s_and_saveexec_b64 s[4:5], s[14:15]
	ds_write_b32 v145, v97
	s_or_b64 exec, exec, s[4:5]
	s_waitcnt lgkmcnt(0)
	ds_read_b128 v[204:207], v147 offset:96
	ds_read_b128 v[216:219], v147 offset:64
	ds_read_b128 v[220:223], v147 offset:32
	ds_read_b128 v[224:227], v147
	s_waitcnt lgkmcnt(3)
	v_pk_mul_f32 v[64:65], v[64:65], v[206:207]
	s_waitcnt lgkmcnt(2)
	v_pk_mul_f32 v[60:61], v[60:61], v[218:219]
	s_waitcnt lgkmcnt(1)
	v_pk_mul_f32 v[56:57], v[56:57], v[222:223]
	s_waitcnt lgkmcnt(0)
	v_pk_mul_f32 v[52:53], v[52:53], v[226:227]
	v_pk_mul_f32 v[62:63], v[62:63], v[204:205]
	v_pk_mul_f32 v[58:59], v[58:59], v[216:217]
	v_pk_mul_f32 v[54:55], v[54:55], v[220:221]
	v_pk_mul_f32 v[50:51], v[50:51], v[224:225]
	v_pk_mul_f32 v[48:49], v[48:49], v[206:207]
	v_pk_mul_f32 v[44:45], v[44:45], v[218:219]
	v_pk_mul_f32 v[40:41], v[40:41], v[222:223]
	v_pk_mul_f32 v[36:37], v[36:37], v[226:227]
	v_pk_mul_f32 v[46:47], v[46:47], v[204:205]
	v_pk_mul_f32 v[42:43], v[42:43], v[216:217]
	v_pk_mul_f32 v[38:39], v[38:39], v[220:221]
	v_pk_mul_f32 v[34:35], v[34:35], v[224:225]
	v_pk_mul_f32 v[32:33], v[32:33], v[206:207]
	v_pk_mul_f32 v[28:29], v[28:29], v[218:219]
	v_pk_mul_f32 v[24:25], v[24:25], v[222:223]
	v_pk_mul_f32 v[20:21], v[20:21], v[226:227]
	v_pk_mul_f32 v[30:31], v[30:31], v[204:205]
	v_pk_mul_f32 v[26:27], v[26:27], v[216:217]
	v_pk_mul_f32 v[22:23], v[22:23], v[220:221]
	v_pk_mul_f32 v[18:19], v[18:19], v[224:225]
	v_pk_mul_f32 v[16:17], v[16:17], v[206:207]
	v_pk_mul_f32 v[12:13], v[12:13], v[218:219]
	v_pk_mul_f32 v[8:9], v[8:9], v[222:223]
	v_pk_mul_f32 v[4:5], v[4:5], v[226:227]
	v_pk_mul_f32 v[14:15], v[14:15], v[204:205]
	v_pk_mul_f32 v[10:11], v[10:11], v[216:217]
	v_pk_mul_f32 v[6:7], v[6:7], v[220:221]
	v_pk_mul_f32 v[2:3], v[2:3], v[224:225]

.LBB0_622:
	s_setprio 0
	v_and_b32_e32 v76, 15, v183
	v_bfe_u32 v77, v183, 4, 3
	v_xor_b32_e32 v78, v76, v77
	v_lshrrev_b32_e32 v74, 1, v76
	v_xor_b32_e32 v74, v74, v77
	v_sub_u32_e32 v74, v74, v78
	v_and_b32_e32 v78, 1, v76
	v_lshlrev_b32_e32 v74, 4, v74
	v_lshl_add_u32 v74, v78, 3, v74
	v_lshrrev_b32_e32 v75, 3, v76
	v_lshrrev_b32_e32 v78, 2, v76
	v_sub_u32_e32 v75, v75, v78
	v_lshlrev_b32_e32 v75, 9, v75
	v_and_b32_e32 v78, 7, v76
	v_lshl_add_u32 v75, v78, 3, v75
	v_and_b32_e32 v78, 3, v76
	v_lshlrev_b32_e32 v78, 4, v78
	v_sub_u32_e32 v75, v75, v78
	v_add_u32_e32 v70, v133, v74
	v_add_u32_e32 v71, v198, v74
	v_add_u32_e32 v72, v199, v75
	v_add_u32_e32 v73, v200, v75
	s_waitcnt vmcnt(6)
	v_cvt_pk_bf16_f32 v66, v102, v103
	v_cvt_pk_bf16_f32 v67, v104, v105
	v_cvt_pk_bf16_f32 v68, v98, v99
	v_cvt_pk_bf16_f32 v69, v100, v101
	ds_write_b64 v70, v[66:67]
	ds_write_b64 v70, v[68:69] offset:128
	s_waitcnt vmcnt(4)
	v_cvt_pk_bf16_f32 v66, v110, v111
	v_cvt_pk_bf16_f32 v67, v112, v113
	v_cvt_pk_bf16_f32 v68, v106, v107
	v_cvt_pk_bf16_f32 v69, v108, v109
	ds_write_b64 v71, v[66:67]
	ds_write_b64 v71, v[68:69] offset:128
	s_waitcnt vmcnt(2)
	v_cvt_pk_bf16_f32 v66, v122, v123
	v_cvt_pk_bf16_f32 v67, v124, v125
	v_cvt_pk_bf16_f32 v68, v114, v115
	v_cvt_pk_bf16_f32 v69, v116, v117
	s_cmpk_eq_i32 s97, 0xf000
	ds_write_b64 v72, v[66:67] offset:32768
	ds_write_b64 v72, v[68:69] offset:33792
	s_waitcnt vmcnt(0)
	v_cvt_pk_bf16_f32 v66, v126, v127
	v_cvt_pk_bf16_f32 v67, v128, v129
	v_cvt_pk_bf16_f32 v68, v118, v119
	v_cvt_pk_bf16_f32 v69, v120, v121
	ds_write_b64 v73, v[66:67] offset:32768
	ds_write_b64 v73, v[68:69] offset:33792

; __device__ __forceinline__ int crow(int r, int hi) { return (r & 3) + 8 * (r >> 2) + 4 * hi; }
; __device__ __forceinline__ void qkt(f32x16& p0, f32x16& p1, const char* Ks, const char* Qs, int r32, int hi) {
; #pragma unroll
;     for (int d0 = 0; d0 < 8; ++d0) { const int cb = (d0 * 16 + hi * 8) * 2;
;         const bf16x8 qv = *reinterpret_cast<const bf16x8*>(Qs + KSWZ(r32, cb));
;         const bf16x8 b0 = *reinterpret_cast<const bf16x8*>(Ks + KSWZ(r32, cb));
;         const bf16x8 b1 = *reinterpret_cast<const bf16x8*>(Ks + KSWZ(32 + r32, cb));
;         p0 = __builtin_amdgcn_mfma_f32_32x32x16_bf16(b0, qv, p0, 0, 0, 0);
;         p1 = __builtin_amdgcn_mfma_f32_32x32x16_bf16(b1, qv, p1, 0, 0, 0); }
; }
; template <int MODE, bool SAMPLE>
; __device__ __forceinline__ void attn_unit(const Params& p, char* lds, int b, int h, int qb) {
;     ...
;         if (wact && j <= jd && var < 2) {
;             const char* Kt = K_lds + buf * 16384; const int vb = vb0 + buf * 16384;
;             f32x16 p0, p1; bf16x8 pa0, pa1, pa2, pa3;
;             if (MODE == 0) {
;                 const float* bt = biasL + j * 64 + 4 * hi;
; #pragma unroll
;                 for (int g = 0; g < 4; ++g) { const f32x4 a = *(const f32x4*)(bt + 8 * g), c = *(const f32x4*)(bt + 32 + 8 * g);
; #pragma unroll
;                     for (int i = 0; i < 4; ++i) { p0[4 * g + i] = a[i]; p1[4 * g + i] = c[i]; } }
;                 qkt(p0, p1, Kt, Qs, r32, hi);
;                 if (j == jd) {
; #pragma unroll
;                     for (int r = 0; r < 16; ++r) { const int kp = j * 64 + crow(r, hi); if (kp > qpos) p0[r] = -1e30f; if (kp + 32 > qpos) p1[r] = -1e30f; } }
.LBB0_624:
	s_and_b64 vcc, exec, s[0:1]
	v_add_u32_e32 v202, 0, v182
	v_add_u32_e32 v203, 0, v184
	v_add_u32_e32 v204, 0, v185
	v_add_u32_e32 v205, 0, v186
	v_add_u32_e32 v206, 0, v187
	v_add_u32_e32 v207, 0, v188
	v_add_u32_e32 v208, 0, v189
	v_add_u32_e32 v209, 0, v190
	s_waitcnt lgkmcnt(0)
	s_barrier
	s_cbranch_vccnz .LBB0_614
	s_setprio 2
	v_add_u32_e32 v94, s97, v214
	v_add_u32_e32 v66, 0x11000, v94
	v_add_u32_e32 v70, 0x11080, v94
	ds_read_b128 v[66:69], v66
	ds_read_b128 v[82:85], v70
	v_add_u32_e32 v70, 0x11020, v94
	v_add_u32_e32 v74, 0x11040, v94
	v_add_u32_e32 v78, 0x11060, v94
	ds_read_b128 v[70:73], v70
	ds_read_b128 v[74:77], v74
	ds_read_b128 v[78:81], v78
	v_add_u32_e32 v86, 0x110a0, v94
	v_add_u32_e32 v95, 0x110c0, v94
	v_add_u32_e32 v94, 0x110e0, v94
	ds_read_b128 v[86:89], v86
	ds_read_b128 v[90:93], v95
	ds_read_b128 v[94:97], v94
	s_cmp_lg_u32 s97, 0
	v_add_u32_e32 v165, s33, v182
	ds_read_b128 v[220:223], v165
	ds_read_b128 v[216:219], v202
	ds_read_b128 v[246:249], v202 offset:8192
	v_add_u32_e32 v165, s33, v184
	ds_read_b128 v[234:237], v165
	ds_read_b128 v[238:241], v203
	ds_read_b128 v[242:245], v203 offset:8192
	s_waitcnt lgkmcnt(4)
	v_mfma_f32_32x32x16_bf16 v[66:81], v[216:219], v[220:223], v[66:81]
	s_waitcnt lgkmcnt(3)
	v_mfma_f32_32x32x16_bf16 v[82:97], v[246:249], v[220:223], v[82:97]
	v_add_u32_e32 v165, s33, v185
	ds_read_b128 v[220:223], v165
	ds_read_b128 v[216:219], v204
	ds_read_b128 v[246:249], v204 offset:8192
	s_waitcnt lgkmcnt(4)
	v_mfma_f32_32x32x16_bf16 v[66:81], v[238:241], v[234:237], v[66:81]
	s_waitcnt lgkmcnt(3)
	v_mfma_f32_32x32x16_bf16 v[82:97], v[242:245], v[234:237], v[82:97]
	v_add_u32_e32 v165, s33, v186
	ds_read_b128 v[234:237], v165
	ds_read_b128 v[238:241], v205
	ds_read_b128 v[242:245], v205 offset:8192
	s_waitcnt lgkmcnt(4)
	v_mfma_f32_32x32x16_bf16 v[66:81], v[216:219], v[220:223], v[66:81]
	s_waitcnt lgkmcnt(3)
	v_mfma_f32_32x32x16_bf16 v[82:97], v[246:249], v[220:223], v[82:97]
	v_add_u32_e32 v165, s33, v187
	ds_read_b128 v[220:223], v165
	ds_read_b128 v[216:219], v206
	ds_read_b128 v[246:249], v206 offset:8192
	s_waitcnt lgkmcnt(4)
	v_mfma_f32_32x32x16_bf16 v[66:81], v[238:241], v[234:237], v[66:81]
	s_waitcnt lgkmcnt(3)
	v_mfma_f32_32x32x16_bf16 v[82:97], v[242:245], v[234:237], v[82:97]
	v_add_u32_e32 v165, s33, v188
	ds_read_b128 v[234:237], v165
	ds_read_b128 v[238:241], v207
	ds_read_b128 v[242:245], v207 offset:8192
	s_waitcnt lgkmcnt(4)
	v_mfma_f32_32x32x16_bf16 v[66:81], v[216:219], v[220:223], v[66:81]
	s_waitcnt lgkmcnt(3)
	v_mfma_f32_32x32x16_bf16 v[82:97], v[246:249], v[220:223], v[82:97]
	v_add_u32_e32 v165, s33, v189
	ds_read_b128 v[220:223], v165
	ds_read_b128 v[216:219], v208
	ds_read_b128 v[246:249], v208 offset:8192
	s_waitcnt lgkmcnt(4)
	v_mfma_f32_32x32x16_bf16 v[66:81], v[238:241], v[234:237], v[66:81]
	s_waitcnt lgkmcnt(3)
	v_mfma_f32_32x32x16_bf16 v[82:97], v[242:245], v[234:237], v[82:97]
	v_add_u32_e32 v165, s33, v190
	ds_read_b128 v[234:237], v165
	ds_read_b128 v[238:241], v209
	ds_read_b128 v[242:245], v209 offset:8192
	s_waitcnt lgkmcnt(4)
	v_mfma_f32_32x32x16_bf16 v[66:81], v[216:219], v[220:223], v[66:81]
	s_waitcnt lgkmcnt(3)
	v_mfma_f32_32x32x16_bf16 v[82:97], v[246:249], v[220:223], v[82:97]
	s_waitcnt lgkmcnt(1)
	v_mfma_f32_32x32x16_bf16 v[66:81], v[238:241], v[234:237], v[66:81]
	s_waitcnt lgkmcnt(0)
	v_mfma_f32_32x32x16_bf16 v[82:97], v[242:245], v[234:237], v[82:97]
	s_nop 1
	s_cbranch_scc1 .LBB0_627
	s_nop 10
	v_mov_b32_e32 v82, 0xf149f2ca
	v_cndmask_b32_e64 v74, v66, v82, s[22:23]
	v_cndmask_b32_e64 v66, v74, v66, s[24:25]
	v_cndmask_b32_e64 v67, v82, v67, s[24:25]
	v_cndmask_b32_e64 v68, v68, v82, s[26:27]
	v_cndmask_b32_e64 v69, v69, v82, s[28:29]
	v_cndmask_b32_e64 v70, v70, v82, s[30:31]
	v_cndmask_b32_e64 v71, v71, v82, s[34:35]
	v_cndmask_b32_e64 v72, v72, v82, s[16:17]
	v_cndmask_b32_e64 v73, v73, v82, s[88:89]
	v_mov_b32_e32 v83, v82
	v_mov_b32_e32 v84, v82
	v_mov_b32_e32 v85, v82
	v_mov_b32_e32 v86, v82
	v_mov_b32_e32 v87, v82
	v_mov_b32_e32 v88, v82
	v_mov_b32_e32 v89, v82
	v_mov_b32_e32 v90, v82
	v_mov_b32_e32 v91, v82
	v_mov_b32_e32 v92, v82
	v_mov_b32_e32 v93, v82
	v_mov_b32_e32 v94, v82
	v_mov_b32_e32 v95, v82
	v_mov_b32_e32 v96, v82
	v_mov_b32_e32 v97, v82
	v_mov_b32_e32 v74, v82
	v_mov_b32_e32 v75, v82
	v_mov_b32_e32 v76, v82
	v_mov_b32_e32 v77, v82
	v_mov_b32_e32 v78, v82
	v_mov_b32_e32 v79, v82
	v_mov_b32_e32 v80, v82
	v_mov_b32_e32 v81, v82

; template <int MODE, bool SAMPLE>
; __device__ __forceinline__ void attn_unit(const Params& p, char* lds, int b, int h, int qb) {
;     ...
; #pragma unroll
;     ...
;         const int j = 2 * jj + par;
;         if (j > jfirst) continue;
;         const int buf = par;
;         WRITET(buf, stg2[NS == 2 ? par : 0]);
;         if (j >= NS) LOADT(j - NS, stg2[NS == 2 ? par : 0]);
;         __syncthreads();
;         if (wact && j <= jd && var < 2) {
.LBB0_638:
	s_setprio 0
	s_add_i32 s9, s9, -1
	s_addk_i32 s54, 0xff80
	s_add_u32 s4, s4, 0xfff80000
	s_addc_u32 s5, s5, -1
	s_cmp_eq_u32 s9, -1
	s_cbranch_scc1 .LBB0_647
.LBB0_639:
	v_cndmask_b32_e64 v66, 0, 1, s[72:73]
	s_cmp_lt_u32 s9, 8
	v_cmp_ne_u32_e64 s[0:1], 1, v66
	s_cbranch_scc0 .Lfsr_first_s1
	v_and_b32_e32 v76, 15, v183
	v_bfe_u32 v77, v183, 4, 3
	v_xor_b32_e32 v78, v76, v77
	v_lshrrev_b32_e32 v74, 1, v76
	v_xor_b32_e32 v74, v74, v77
	v_sub_u32_e32 v74, v74, v78
	v_and_b32_e32 v78, 1, v76
	v_lshlrev_b32_e32 v74, 4, v74
	v_lshl_add_u32 v74, v78, 3, v74
	v_lshrrev_b32_e32 v75, 3, v76
	v_lshrrev_b32_e32 v78, 2, v76
	v_sub_u32_e32 v75, v75, v78
	v_lshlrev_b32_e32 v75, 9, v75
	v_and_b32_e32 v78, 7, v76
	v_lshl_add_u32 v75, v78, 3, v75
	v_and_b32_e32 v78, 3, v76
	v_lshlrev_b32_e32 v78, 4, v78
	v_sub_u32_e32 v75, v75, v78
	v_add_u32_e32 v70, v133, v74
	v_add_u32_e32 v71, v198, v74
	v_add_u32_e32 v72, v199, v75
	v_add_u32_e32 v73, v200, v75
	s_waitcnt vmcnt(6)
	v_cvt_pk_bf16_f32 v66, v102, v103
	v_cvt_pk_bf16_f32 v67, v104, v105
	v_cvt_pk_bf16_f32 v68, v98, v99
	v_cvt_pk_bf16_f32 v69, v100, v101
	ds_write_b64 v70, v[66:67] offset:16384
	ds_write_b64 v70, v[68:69] offset:16512
	s_waitcnt vmcnt(4)
	v_cvt_pk_bf16_f32 v66, v110, v111
	v_cvt_pk_bf16_f32 v67, v112, v113
	v_cvt_pk_bf16_f32 v68, v106, v107
	v_cvt_pk_bf16_f32 v69, v108, v109
	ds_write_b64 v71, v[66:67] offset:16384
	ds_write_b64 v71, v[68:69] offset:16512
	s_waitcnt vmcnt(2)
	v_cvt_pk_bf16_f32 v66, v118, v119
	v_cvt_pk_bf16_f32 v67, v120, v121
	v_cvt_pk_bf16_f32 v68, v114, v115
	v_cvt_pk_bf16_f32 v69, v116, v117
	ds_write_b64 v72, v[66:67] offset:49152
	ds_write_b64 v72, v[68:69] offset:50176
	s_waitcnt vmcnt(0)
	v_cvt_pk_bf16_f32 v66, v126, v127
	v_cvt_pk_bf16_f32 v67, v128, v129
	v_cvt_pk_bf16_f32 v68, v122, v123
	v_cvt_pk_bf16_f32 v69, v124, v125
	ds_write_b64 v73, v[66:67] offset:49152
	ds_write_b64 v73, v[68:69] offset:50176
	v_lshl_add_u64 v[66:67], v[168:169], 0, s[4:5]
	v_and_b32_e32 v72, 15, v183
	v_lshlrev_b32_e32 v72, 4, v72
	v_sub_co_u32_e32 v66, vcc, v66, v72
	s_nop 1
	v_subbrev_co_u32_e32 v67, vcc, 0, v67, vcc
	v_add_co_u32_e32 v70, vcc, s86, v66
	v_lshl_add_u64 v[68:69], v[66:67], 0, s[58:59]
	s_nop 0
	v_addc_co_u32_e32 v71, vcc, 0, v67, vcc
	s_mov_b32 s6, 0x420000
	global_load_dwordx4 v[102:105], v[70:71], off nt
	global_load_dwordx4 v[98:101], v[68:69], off offset:256 nt
	v_lshl_add_u64 v[68:69], v[66:67], 0, s[60:61]
	v_add_co_u32_e32 v66, vcc, s6, v66
	s_nop 1
	v_addc_co_u32_e32 v67, vcc, 0, v67, vcc
	global_load_dwordx4 v[110:113], v[66:67], off nt
	global_load_dwordx4 v[106:109], v[68:69], off offset:256 nt
	v_lshl_add_u64 v[66:67], v[170:171], 0, s[4:5]
	v_and_b32_e32 v72, 15, v183
	v_lshlrev_b32_e32 v72, 4, v72
	v_sub_co_u32_e32 v66, vcc, v66, v72
	s_nop 1
	v_subbrev_co_u32_e32 v67, vcc, 0, v67, vcc
	v_add_co_u32_e32 v70, vcc, s86, v66
	v_lshl_add_u64 v[68:69], v[66:67], 0, s[58:59]
	s_nop 0
	v_addc_co_u32_e32 v71, vcc, 0, v67, vcc
	global_load_dwordx4 v[118:121], v[70:71], off nt
	global_load_dwordx4 v[114:117], v[68:69], off offset:256 nt
	v_lshl_add_u64 v[68:69], v[66:67], 0, s[60:61]
	v_add_co_u32_e32 v66, vcc, 0x420000, v66
	s_nop 1
	v_addc_co_u32_e32 v67, vcc, 0, v67, vcc
	global_load_dwordx4 v[126:129], v[66:67], off nt
	global_load_dwordx4 v[122:125], v[68:69], off offset:256 nt
	s_and_b64 vcc, exec, s[0:1]
	s_waitcnt lgkmcnt(0)
	s_barrier
	s_cbranch_vccnz .LBB0_642
	s_setprio 2
	ds_read_b128 v[66:69], v202 offset:16384
	v_add_u32_e32 v70, s8, v182
	ds_read_b128 v[70:73], v70
	ds_read_b128 v[74:77], v202 offset:24576
	v_add_u32_e32 v78, s8, v184
	ds_read_b128 v[216:219], v78
	ds_read_b128 v[220:223], v203 offset:16384
	ds_read_b128 v[224:227], v203 offset:24576
	v_add_u32_e32 v147, s8, v185
	s_waitcnt lgkmcnt(4)
	v_mfma_f32_32x32x16_bf16 v[82:97], v[66:69], v[70:73], 0
	s_waitcnt lgkmcnt(3)
	v_mfma_f32_32x32x16_bf16 v[66:81], v[74:77], v[70:73], 0
	s_waitcnt lgkmcnt(1)
	v_mfma_f32_32x32x16_bf16 v[82:97], v[220:223], v[216:219], v[82:97]
	s_waitcnt lgkmcnt(0)
	v_mfma_f32_32x32x16_bf16 v[66:81], v[224:227], v[216:219], v[66:81]
	ds_read_b128 v[216:219], v204 offset:16384
	ds_read_b128 v[220:223], v147
	ds_read_b128 v[224:227], v204 offset:24576
	v_add_u32_e32 v147, s8, v186
	ds_read_b128 v[228:231], v147
	v_add_u32_e32 v147, s8, v187
	s_waitcnt lgkmcnt(2)
	v_mfma_f32_32x32x16_bf16 v[82:97], v[216:219], v[220:223], v[82:97]
	s_waitcnt lgkmcnt(1)
	v_mfma_f32_32x32x16_bf16 v[66:81], v[224:227], v[220:223], v[66:81]
	ds_read_b128 v[216:219], v205 offset:16384
	ds_read_b128 v[220:223], v205 offset:24576
	s_waitcnt lgkmcnt(1)
	v_mfma_f32_32x32x16_bf16 v[82:97], v[216:219], v[228:231], v[82:97]
	ds_read_b128 v[216:219], v206 offset:16384
	s_waitcnt lgkmcnt(1)
	v_mfma_f32_32x32x16_bf16 v[66:81], v[220:223], v[228:231], v[66:81]
	ds_read_b128 v[220:223], v147
	ds_read_b128 v[224:227], v206 offset:24576
	v_add_u32_e32 v147, s8, v188
	ds_read_b128 v[228:231], v147
	v_add_u32_e32 v147, s8, v189
	s_waitcnt lgkmcnt(1)
	v_mfma_f32_32x32x16_bf16 v[66:81], v[224:227], v[220:223], v[66:81]
	v_mfma_f32_32x32x16_bf16 v[82:97], v[216:219], v[220:223], v[82:97]
	ds_read_b128 v[216:219], v207 offset:16384
	ds_read_b128 v[220:223], v207 offset:24576
	s_waitcnt lgkmcnt(0)
	v_mfma_f32_32x32x16_bf16 v[66:81], v[220:223], v[228:231], v[66:81]
	v_mfma_f32_32x32x16_bf16 v[82:97], v[216:219], v[228:231], v[82:97]
	ds_read_b128 v[216:219], v208 offset:16384
	ds_read_b128 v[220:223], v147
	ds_read_b128 v[224:227], v208 offset:24576
	v_add_u32_e32 v147, s8, v190
	ds_read_b128 v[228:231], v147
	s_waitcnt lgkmcnt(1)
; __device__ __forceinline__ int crow(int r, int hi) { return (r & 3) + 8 * (r >> 2) + 4 * hi; }
; __device__ __forceinline__ void qkt(f32x16& p0, f32x16& p1, const char* Ks, const char* Qs, int r32, int hi) {
; #pragma unroll
;     for (int d0 = 0; d0 < 8; ++d0) { const int cb = (d0 * 16 + hi * 8) * 2;
;         const bf16x8 qv = *reinterpret_cast<const bf16x8*>(Qs + KSWZ(r32, cb));
;         const bf16x8 b0 = *reinterpret_cast<const bf16x8*>(Ks + KSWZ(r32, cb));
;         const bf16x8 b1 = *reinterpret_cast<const bf16x8*>(Ks + KSWZ(32 + r32, cb));
;         p0 = __builtin_amdgcn_mfma_f32_32x32x16_bf16(b0, qv, p0, 0, 0, 0);
;         p1 = __builtin_amdgcn_mfma_f32_32x32x16_bf16(b1, qv, p1, 0, 0, 0); }
; template <int MODE, bool SAMPLE>
; __device__ __forceinline__ void attn_unit(const Params& p, char* lds, int b, int h, int qb) {
;     ...
;                 p0 = f32x16{}; p1 = f32x16{};
;                 qkt(p0, p1, Kt, Qs, r32, hi);
;                 if (j == jd) {
; #pragma unroll
;                     for (int r = 0; r < 16; ++r) { const int kp = j * 64 + crow(r, hi); if (kp >= qpos) p0[r] = -1e30f; if (kp + 32 >= qpos) p1[r] = -1e30f; } }
;                 f32x16 s0, s1;
; #pragma unroll
;                 for (int r = 0; r < 16; ++r) { p0[r] = __builtin_amdgcn_exp2f(fminf(p0[r], 100.f)); p1[r] = __builtin_amdgcn_exp2f(fminf(p1[r], 100.f));
;                     s0[r] = __builtin_amdgcn_rcpf(1.f + p0[r]); s1[r] = __builtin_amdgcn_rcpf(1.f + p1[r]); }
;                 float run = carry, bs[8];
; #pragma unroll
;                 for (int i = 7; i >= 0; --i) { const f32x16& S = (i >= 4) ? s1 : s0; const int rb = 4 * (i & 3);
;                     const float gs = (S[rb] * S[rb + 1]) * (S[rb + 2] * S[rb + 3]);
;                     auto rr = __builtin_amdgcn_permlane32_swap(__float_as_uint(gs), __float_as_uint(gs), false, false);
;                     const float glo = __uint_as_float(rr[0]), ghi = __uint_as_float(rr[1]);
;                     const float exH = run; run *= ghi; const float exL = run; run *= glo;
;                     bs[i] = hi ? exH : exL; }
;                 carry = run;
	v_mfma_f32_32x32x16_bf16 v[66:81], v[224:227], v[220:223], v[66:81]
	v_mfma_f32_32x32x16_bf16 v[82:97], v[216:219], v[220:223], v[82:97]
	ds_read_b128 v[216:219], v209 offset:16384
	ds_read_b128 v[220:223], v209 offset:24576
	s_waitcnt lgkmcnt(0)
	v_mfma_f32_32x32x16_bf16 v[66:81], v[220:223], v[228:231], v[66:81]
	v_mfma_f32_32x32x16_bf16 v[82:97], v[216:219], v[228:231], v[82:97]
	s_nop 10
	v_max_f32_e32 v69, v69, v69
	v_min_f32_e32 v69, 0x42c80000, v69
	v_exp_f32_e32 v219, v69
	v_max_f32_e32 v81, v81, v81
	v_min_f32_e32 v81, 0x42c80000, v81
	v_max_f32_e32 v68, v68, v68
	v_max_f32_e32 v66, v66, v66
	v_max_f32_e32 v69, v86, v86
	v_min_f32_e32 v69, 0x42c80000, v69
	v_exp_f32_e32 v86, v69
	v_max_f32_e32 v69, v70, v70
	v_max_f32_e32 v70, v87, v87
	v_min_f32_e32 v70, 0x42c80000, v70
	v_exp_f32_e32 v87, v70
	v_max_f32_e32 v70, v71, v71
	v_max_f32_e32 v71, v88, v88
	v_min_f32_e32 v71, 0x42c80000, v71
	v_exp_f32_e32 v88, v71
	v_max_f32_e32 v71, v72, v72
	v_max_f32_e32 v72, v89, v89
	v_min_f32_e32 v72, 0x42c80000, v72
	v_exp_f32_e32 v89, v72
	v_max_f32_e32 v72, v73, v73
	v_max_f32_e32 v73, v90, v90
	v_min_f32_e32 v73, 0x42c80000, v73
	v_exp_f32_e32 v90, v73
	v_max_f32_e32 v73, v74, v74
	v_max_f32_e32 v74, v91, v91
	v_min_f32_e32 v74, 0x42c80000, v74
	v_exp_f32_e32 v91, v74
	v_max_f32_e32 v74, v75, v75
	v_max_f32_e32 v75, v92, v92
	v_min_f32_e32 v75, 0x42c80000, v75
	v_exp_f32_e32 v92, v75
	v_max_f32_e32 v75, v76, v76
	v_max_f32_e32 v76, v93, v93
	v_min_f32_e32 v76, 0x42c80000, v76
	v_exp_f32_e32 v93, v76
	v_max_f32_e32 v76, v77, v77
	v_max_f32_e32 v77, v94, v94
	v_min_f32_e32 v77, 0x42c80000, v77
	v_exp_f32_e32 v94, v77
	v_max_f32_e32 v77, v78, v78
	v_max_f32_e32 v78, v95, v95
	v_min_f32_e32 v78, 0x42c80000, v78
	v_exp_f32_e32 v95, v78
	v_max_f32_e32 v78, v79, v79
	v_max_f32_e32 v79, v96, v96
	v_min_f32_e32 v79, 0x42c80000, v79
	v_min_f32_e32 v77, 0x42c80000, v77
	v_exp_f32_e32 v96, v79
	v_max_f32_e32 v79, v80, v80
	v_exp_f32_e32 v237, v77
	v_min_f32_e32 v79, 0x42c80000, v79
	v_min_f32_e32 v78, 0x42c80000, v78
	v_exp_f32_e32 v241, v79
	v_exp_f32_e32 v239, v78
	v_max_f32_e32 v80, v97, v97
	v_exp_f32_e32 v97, v81
	v_min_f32_e32 v73, 0x42c80000, v73
	v_add_f32_e32 v77, 1.0, v237
	v_exp_f32_e32 v229, v73
	v_rcp_f32_e32 v240, v77
	v_add_f32_e32 v77, 1.0, v95
	v_add_f32_e32 v79, 1.0, v241
	v_min_f32_e32 v74, 0x42c80000, v74
	v_min_f32_e32 v75, 0x42c80000, v75
	v_min_f32_e32 v76, 0x42c80000, v76
	v_rcp_f32_e32 v78, v77
	v_add_f32_e32 v77, 1.0, v239
	v_rcp_f32_e32 v244, v79
	v_add_f32_e32 v79, 1.0, v97
	v_exp_f32_e32 v231, v74
	v_exp_f32_e32 v233, v75
	v_exp_f32_e32 v235, v76
	v_rcp_f32_e32 v242, v77
	v_rcp_f32_e32 v245, v79
	v_min_f32_e32 v69, 0x42c80000, v69
	v_add_f32_e32 v73, 1.0, v229
	v_max_f32_e32 v83, v83, v83
	v_exp_f32_e32 v221, v69
	v_rcp_f32_e32 v232, v73
	v_add_f32_e32 v73, 1.0, v91
	v_min_f32_e32 v80, 0x42c80000, v80
	v_min_f32_e32 v83, 0x42c80000, v83
	v_min_f32_e32 v70, 0x42c80000, v70
	v_min_f32_e32 v71, 0x42c80000, v71
	v_min_f32_e32 v72, 0x42c80000, v72
	v_rcp_f32_e32 v74, v73
	v_add_f32_e32 v73, 1.0, v231
	v_add_f32_e32 v75, 1.0, v233
	v_add_f32_e32 v76, 1.0, v235
	v_exp_f32_e32 v243, v80
	v_mul_f32_e32 v80, v240, v242
	v_mul_f32_e32 v81, v244, v245
	v_exp_f32_e32 v165, v83
	v_max_f32_e32 v83, v84, v84
	v_exp_f32_e32 v223, v70
	v_exp_f32_e32 v225, v71
	v_exp_f32_e32 v227, v72
	v_rcp_f32_e32 v234, v73
	v_rcp_f32_e32 v236, v75
	v_rcp_f32_e32 v238, v76
	v_mul_f32_e32 v80, v80, v81
	v_min_f32_e32 v83, 0x42c80000, v83
	v_mov_b32_e32 v81, v80
	v_exp_f32_e32 v84, v83
	v_min_f32_e32 v68, 0x42c80000, v68
	v_max_f32_e32 v83, v85, v85
	v_add_f32_e32 v69, 1.0, v221
	v_permlane32_swap_b32_e32 v80, v81
	v_min_f32_e32 v66, 0x42c80000, v66
	v_max_f32_e32 v67, v67, v67
	v_exp_f32_e32 v217, v68
	v_min_f32_e32 v83, 0x42c80000, v83
	v_rcp_f32_e32 v224, v69
	v_add_f32_e32 v69, 1.0, v87
	v_mul_f32_e32 v81, v145, v81
	v_exp_f32_e32 v163, v66
	v_min_f32_e32 v67, 0x42c80000, v67
	v_exp_f32_e32 v85, v83
	v_rcp_f32_e32 v70, v69
	v_add_f32_e32 v69, 1.0, v223
	v_add_f32_e32 v71, 1.0, v225
	v_add_f32_e32 v72, 1.0, v227
	v_mul_f32_e32 v80, v81, v80
	v_cndmask_b32_e64 v145, v145, v81, s[14:15]
	v_mul_f32_e32 v81, v232, v234
	v_mul_f32_e32 v246, v236, v238
	v_exp_f32_e32 v215, v67
	v_rcp_f32_e32 v226, v69
	v_rcp_f32_e32 v228, v71
	v_rcp_f32_e32 v230, v72
	v_mul_f32_e32 v81, v81, v246
	v_max_f32_e32 v82, v82, v82
	v_mov_b32_e32 v246, v81
	v_min_f32_e32 v82, 0x42c80000, v82
	v_add_f32_e32 v68, 1.0, v217
	v_permlane32_swap_b32_e32 v81, v246
	v_exp_f32_e32 v147, v82
	v_add_f32_e32 v82, 1.0, v163
	v_add_f32_e32 v67, 1.0, v165
	v_rcp_f32_e32 v220, v68
	v_add_f32_e32 v68, 1.0, v85
	v_mul_f32_e32 v246, v80, v246
	v_rcp_f32_e32 v216, v82
	v_rcp_f32_e32 v82, v67
	v_add_f32_e32 v67, 1.0, v215
	v_rcp_f32_e32 v83, v68
	v_add_f32_e32 v68, 1.0, v219
	v_mul_f32_e32 v81, v246, v81
	v_cndmask_b32_e64 v246, v80, v246, s[14:15]
	v_mul_f32_e32 v80, v224, v226
	v_mul_f32_e32 v247, v228, v230
	v_rcp_f32_e32 v218, v67
	v_rcp_f32_e32 v222, v68
	v_mul_f32_e32 v80, v80, v247
	v_mov_b32_e32 v247, v80
	s_nop 1
	v_permlane32_swap_b32_e32 v80, v247
	v_mul_f32_e32 v247, v81, v247
	v_add_f32_e32 v76, 1.0, v94
	v_add_f32_e32 v77, 1.0, v96
	v_add_f32_e32 v79, 1.0, v243
	v_mul_f32_e32 v80, v247, v80
	v_cndmask_b32_e64 v247, v81, v247, s[14:15]
	v_mul_f32_e32 v81, v216, v218
	v_mul_f32_e32 v248, v220, v222
	v_rcp_f32_e32 v76, v76
	v_rcp_f32_e32 v77, v77
	v_rcp_f32_e32 v79, v79
	v_mul_f32_e32 v81, v81, v248
	v_mov_b32_e32 v248, v81
	s_nop 1
	v_permlane32_swap_b32_e32 v81, v248
	v_mul_f32_e32 v248, v80, v248
	v_add_f32_e32 v72, 1.0, v90
	v_add_f32_e32 v73, 1.0, v92
	v_add_f32_e32 v75, 1.0, v93
; #define SBAR() __builtin_amdgcn_sched_barrier(0)
; template <int OFF> __device__ __forceinline__ s16x4 tr_read(int vb) { s16x4 r; asm volatile("ds_read_b64_tr_b16 %0, %1 offset:%2" : "=&v"(r) : "v"(vb), "i"(OFF) : "memory"); return r; }
; template <int D0> __device__ __forceinline__ void pv_one(f32x16& od, int vb, bf16x8 pa0, bf16x8 pa1, bf16x8 pa2, bf16x8 pa3) {
;     const s16x4 l0 = tr_read<v_rd_off(D0, 0, 0)>(vb), h0 = tr_read<v_rd_off(D0, 0, 1)>(vb), l1 = tr_read<v_rd_off(D0, 1, 0)>(vb), h1 = tr_read<v_rd_off(D0, 1, 1)>(vb);
;     const s16x4 l2 = tr_read<v_rd_off(D0, 2, 0)>(vb), h2 = tr_read<v_rd_off(D0, 2, 1)>(vb), l3 = tr_read<v_rd_off(D0, 3, 0)>(vb), h3 = tr_read<v_rd_off(D0, 3, 1)>(vb);
;     asm volatile("s_waitcnt lgkmcnt(0)" ::: "memory"); SBAR();
;     ...
;     od = __builtin_amdgcn_mfma_f32_32x32x16_bf16(pa0, PKV(l0, h0), od, 0, 0, 0);
;     od = __builtin_amdgcn_mfma_f32_32x32x16_bf16(pa1, PKV(l1, h1), od, 0, 0, 0);
;     od = __builtin_amdgcn_mfma_f32_32x32x16_bf16(pa2, PKV(l2, h2), od, 0, 0, 0);
;     od = __builtin_amdgcn_mfma_f32_32x32x16_bf16(pa3, PKV(l3, h3), od, 0, 0, 0);
;     ...
; }
; __device__ __forceinline__ void pv_d0(f32x16* o, int vb, bf16x8 pa0, bf16x8 pa1, bf16x8 pa2, bf16x8 pa3) {
;     pv_one<0>(o[0], vb, pa0, pa1, pa2, pa3); pv_one<1>(o[1], vb, pa0, pa1, pa2, pa3); pv_one<2>(o[2], vb, pa0, pa1, pa2, pa3); pv_one<3>(o[3], vb, pa0, pa1, pa2, pa3);
; }
; template <int MODE, bool SAMPLE>
; __device__ __forceinline__ void attn_unit(const Params& p, char* lds, int b, int h, int qb) {
;     ...
;                 carry = run;
; #pragma unroll
;                 for (int i = 0; i < 8; ++i) { f32x16& S = (i >= 4) ? s1 : s0; f32x16& Z = (i >= 4) ? p1 : p0; const int rb = 4 * (i & 3);
;                     const float i3 = bs[i] * S[rb + 3], i2 = i3 * S[rb + 2], i1 = i2 * S[rb + 1], i0 = i1 * S[rb];
;                     Z[rb + 3] *= i3; Z[rb + 2] *= i2; Z[rb + 1] *= i1; Z[rb] *= i0; }
;             }
;             PK4(p0, 0, pa0); PK4(p0, 8, pa1); PK4(p1, 0, pa2); PK4(p1, 8, pa3);
;             pv_d0(o, vb, pa0, pa1, pa2, pa3);
	v_mul_f32_e32 v249, v248, v81
	v_cndmask_b32_e64 v248, v80, v248, s[14:15]
	v_pk_mul_f32 v[80:81], v[76:77], v[78:79]
	v_rcp_f32_e32 v72, v72
	v_rcp_f32_e32 v73, v73
	v_rcp_f32_e32 v75, v75
	v_pk_mul_f32 v[80:81], v[80:81], v[80:81] op_sel:[0,1] op_sel_hi:[1,0]
	v_add_f32_e32 v68, 1.0, v86
	v_mov_b32_e32 v81, v80
	s_nop 1
	v_permlane32_swap_b32_e32 v80, v81
	v_mul_f32_e32 v81, v249, v81
	v_add_f32_e32 v69, 1.0, v88
	v_add_f32_e32 v71, 1.0, v89
	v_mul_f32_e32 v250, v81, v80
	v_cndmask_b32_e64 v249, v249, v81, s[14:15]
	v_pk_mul_f32 v[80:81], v[72:73], v[74:75]
	v_rcp_f32_e32 v68, v68
	v_rcp_f32_e32 v69, v69
	v_rcp_f32_e32 v71, v71
	v_pk_mul_f32 v[80:81], v[80:81], v[80:81] op_sel:[0,1] op_sel_hi:[1,0]
	v_add_f32_e32 v66, 1.0, v147
	v_mov_b32_e32 v81, v80
	s_nop 1
	v_permlane32_swap_b32_e32 v80, v81
	v_mul_f32_e32 v81, v250, v81
	v_add_f32_e32 v67, 1.0, v84
	v_mul_f32_e32 v251, v81, v80
	v_cndmask_b32_e64 v250, v250, v81, s[14:15]
	v_pk_mul_f32 v[80:81], v[68:69], v[70:71]
	v_rcp_f32_e32 v66, v66
	v_rcp_f32_e32 v67, v67
	v_pk_mul_f32 v[80:81], v[80:81], v[80:81] op_sel:[0,1] op_sel_hi:[1,0]
	v_mul_f32_e32 v75, v75, v250
	v_mov_b32_e32 v81, v80
	s_nop 1
	v_permlane32_swap_b32_e32 v80, v81
	v_mul_f32_e32 v81, v251, v81
	v_mul_f32_e32 v252, v81, v80
	v_cndmask_b32_e64 v251, v251, v81, s[14:15]
	v_pk_mul_f32 v[80:81], v[66:67], v[82:83]
	v_mul_f32_e32 v71, v71, v251
	v_pk_mul_f32 v[80:81], v[80:81], v[80:81] op_sel:[0,1] op_sel_hi:[1,0]
	v_mul_f32_e32 v69, v69, v71
	v_mov_b32_e32 v81, v80
	s_nop 1
	v_permlane32_swap_b32_e32 v80, v81
	v_mul_f32_e32 v81, v252, v81
	v_cndmask_b32_e64 v252, v252, v81, s[14:15]
	v_mul_f32_e32 v83, v83, v252
	v_mul_f32_e32 v67, v67, v83
	v_mul_f32_e32 v79, v79, v249
	v_mul_f32_e32 v82, v82, v67
	v_mul_f32_e32 v67, v84, v67
	v_mul_f32_e32 v70, v70, v69
	v_mul_f32_e32 v73, v73, v75
	v_mul_f32_e32 v77, v77, v79
	v_mul_f32_e32 v84, v222, v248
	v_mul_f32_e32 v83, v85, v83
	v_mul_f32_e32 v68, v68, v70
	v_mul_f32_e32 v69, v88, v69
	v_mul_f32_e32 v74, v74, v73
	v_mul_f32_e32 v73, v92, v73
	v_mul_f32_e32 v78, v78, v77
	v_mul_f32_e32 v77, v96, v77
	v_mul_f32_e32 v85, v220, v84
	v_mul_f32_e32 v88, v230, v247
	v_mul_f32_e32 v92, v238, v246
	v_mul_f32_e32 v96, v245, v145
	v_mul_f32_e32 v66, v66, v82
	v_mul_f32_e32 v71, v89, v71
	v_mul_f32_e32 v68, v86, v68
	v_mul_f32_e32 v72, v72, v74
	v_mul_f32_e32 v75, v93, v75
	v_mul_f32_e32 v76, v76, v78
	v_mul_f32_e32 v86, v218, v85
	v_mul_f32_e32 v89, v228, v88
	v_mul_f32_e32 v93, v236, v92
	v_mul_f32_e32 v145, v244, v96
	v_mul_f32_e32 v66, v147, v66
	v_mul_f32_e32 v70, v87, v70
	v_mul_f32_e32 v72, v90, v72
	v_mul_f32_e32 v76, v94, v76
	v_mul_f32_e32 v87, v216, v86
	v_mul_f32_e32 v90, v226, v89
	v_mul_f32_e32 v94, v234, v93
	v_mul_f32_e32 v147, v242, v145
	v_mul_f32_e32 v82, v165, v82
	v_mul_f32_e32 v74, v91, v74
	v_mul_f32_e32 v79, v243, v79
	v_mul_f32_e32 v78, v95, v78
	v_mul_f32_e32 v87, v163, v87
	v_mul_f32_e32 v91, v224, v90
	v_mul_f32_e32 v95, v232, v94
	v_mul_f32_e32 v163, v240, v147
	v_mul_f32_e32 v84, v219, v84
	v_mul_f32_e32 v85, v217, v85
	v_mul_f32_e32 v86, v215, v86
	v_mul_f32_e32 v88, v227, v88
	v_mul_f32_e32 v89, v225, v89
	v_mul_f32_e32 v90, v223, v90
	v_mul_f32_e32 v91, v221, v91
	v_mul_f32_e32 v92, v235, v92
	v_mul_f32_e32 v93, v233, v93
	v_mul_f32_e32 v94, v231, v94
	v_mul_f32_e32 v95, v229, v95
	v_mul_f32_e32 v96, v97, v96
	v_mul_f32_e32 v97, v241, v145
	v_mul_f32_e32 v147, v239, v147
	v_mul_f32_e32 v163, v237, v163
	v_mul_f32_e32 v145, v81, v80
	v_cvt_pk_bf16_f32 v66, v66, v82
	v_cvt_pk_bf16_f32 v67, v67, v83
	v_cvt_pk_bf16_f32 v68, v68, v70
	v_cvt_pk_bf16_f32 v69, v69, v71
	v_cvt_pk_bf16_f32 v70, v72, v74
	v_cvt_pk_bf16_f32 v71, v73, v75
	v_cvt_pk_bf16_f32 v72, v76, v78
	v_cvt_pk_bf16_f32 v73, v77, v79
	v_cvt_pk_bf16_f32 v74, v87, v86
	v_cvt_pk_bf16_f32 v75, v85, v84
	v_cvt_pk_bf16_f32 v76, v91, v90
	v_cvt_pk_bf16_f32 v77, v89, v88
	v_cvt_pk_bf16_f32 v78, v95, v94
	v_cvt_pk_bf16_f32 v79, v93, v92
	v_cvt_pk_bf16_f32 v80, v163, v147
	v_cvt_pk_bf16_f32 v81, v97, v96
	ds_read_b64_tr_b16 v[82:83], v191 offset:0
	ds_read_b64_tr_b16 v[84:85], v191 offset:0x800
	ds_read_b64_tr_b16 v[86:87], v191 offset:0x1000
	ds_read_b64_tr_b16 v[88:89], v191 offset:0x1800
	ds_read_b64_tr_b16 v[90:91], v191 offset:0x2000
	ds_read_b64_tr_b16 v[92:93], v191 offset:0x2800
	ds_read_b64_tr_b16 v[94:95], v191 offset:0x3000
	ds_read_b64_tr_b16 v[96:97], v191 offset:0x3800
	s_waitcnt lgkmcnt(0)
	s_nop 0
	v_permlane32_swap_b32_e32 v66, v68
	v_permlane32_swap_b32_e32 v67, v69
	v_permlane32_swap_b32_e32 v70, v72
	v_permlane32_swap_b32_e32 v71, v73
	v_permlane32_swap_b32_e32 v74, v76
	v_permlane32_swap_b32_e32 v75, v77
	v_permlane32_swap_b32_e32 v78, v80
	v_permlane32_swap_b32_e32 v79, v81
	v_mfma_f32_32x32x16_bf16 v[2:17], v[66:69], v[82:85], v[2:17]
	ds_read_b64_tr_b16 v[82:83], v191 offset:0x200
	ds_read_b64_tr_b16 v[84:85], v191 offset:0xa00
	v_mfma_f32_32x32x16_bf16 v[2:17], v[70:73], v[86:89], v[2:17]
	ds_read_b64_tr_b16 v[86:87], v191 offset:0x1200
	ds_read_b64_tr_b16 v[88:89], v191 offset:0x1a00
	v_mfma_f32_32x32x16_bf16 v[2:17], v[74:77], v[90:93], v[2:17]
	ds_read_b64_tr_b16 v[90:91], v191 offset:0x2200
	ds_read_b64_tr_b16 v[92:93], v191 offset:0x2a00
	v_mfma_f32_32x32x16_bf16 v[2:17], v[78:81], v[94:97], v[2:17]
	ds_read_b64_tr_b16 v[94:95], v191 offset:0x3200
	ds_read_b64_tr_b16 v[96:97], v191 offset:0x3a00
	s_waitcnt lgkmcnt(0)
	v_mfma_f32_32x32x16_bf16 v[50:65], v[66:69], v[82:85], v[50:65]
	ds_read_b64_tr_b16 v[82:83], v191 offset:0x400
	ds_read_b64_tr_b16 v[84:85], v191 offset:0xc00
	v_mfma_f32_32x32x16_bf16 v[50:65], v[70:73], v[86:89], v[50:65]
	ds_read_b64_tr_b16 v[86:87], v191 offset:0x1400
	ds_read_b64_tr_b16 v[88:89], v191 offset:0x1c00
	v_mfma_f32_32x32x16_bf16 v[50:65], v[74:77], v[90:93], v[50:65]
	ds_read_b64_tr_b16 v[90:91], v191 offset:0x2400
	ds_read_b64_tr_b16 v[92:93], v191 offset:0x2c00
	v_mfma_f32_32x32x16_bf16 v[50:65], v[78:81], v[94:97], v[50:65]
	ds_read_b64_tr_b16 v[94:95], v191 offset:0x3400
	ds_read_b64_tr_b16 v[96:97], v191 offset:0x3c00
	s_waitcnt lgkmcnt(0)
	v_mfma_f32_32x32x16_bf16 v[34:49], v[66:69], v[82:85], v[34:49]
	ds_read_b64_tr_b16 v[82:83], v191 offset:0x600
	ds_read_b64_tr_b16 v[84:85], v191 offset:0xe00
	v_mfma_f32_32x32x16_bf16 v[34:49], v[70:73], v[86:89], v[34:49]
	ds_read_b64_tr_b16 v[86:87], v191 offset:0x1600
	ds_read_b64_tr_b16 v[88:89], v191 offset:0x1e00
	v_mfma_f32_32x32x16_bf16 v[34:49], v[74:77], v[90:93], v[34:49]
	ds_read_b64_tr_b16 v[90:91], v191 offset:0x2600
	ds_read_b64_tr_b16 v[92:93], v191 offset:0x2e00
	v_mfma_f32_32x32x16_bf16 v[34:49], v[78:81], v[94:97], v[34:49]
	ds_read_b64_tr_b16 v[94:95], v191 offset:0x3600
	ds_read_b64_tr_b16 v[96:97], v191 offset:0x3e00
	s_waitcnt lgkmcnt(0)
	v_mfma_f32_32x32x16_bf16 v[18:33], v[66:69], v[82:85], v[18:33]
	v_mfma_f32_32x32x16_bf16 v[18:33], v[70:73], v[86:89], v[18:33]
	v_mfma_f32_32x32x16_bf16 v[18:33], v[74:77], v[90:93], v[18:33]
	v_mfma_f32_32x32x16_bf16 v[18:33], v[78:81], v[94:97], v[18:33]
; template <int MODE, bool SAMPLE>
; __device__ __forceinline__ void attn_unit(const Params& p, char* lds, int b, int h, int qb) {
;     ...
;         WRITET(buf, stg2[NS == 2 ? par : 0]);
;         if (j >= NS) LOADT(j - NS, stg2[NS == 2 ? par : 0]);
.LBB0_642:
	s_setprio 0
	v_and_b32_e32 v76, 15, v183
	v_bfe_u32 v77, v183, 4, 3
	v_xor_b32_e32 v78, v76, v77
	v_lshrrev_b32_e32 v74, 1, v76
	v_xor_b32_e32 v74, v74, v77
	v_sub_u32_e32 v74, v74, v78
	v_and_b32_e32 v78, 1, v76
	v_lshlrev_b32_e32 v74, 4, v74
	v_lshl_add_u32 v74, v78, 3, v74
	v_lshrrev_b32_e32 v75, 3, v76
	v_lshrrev_b32_e32 v78, 2, v76
	v_sub_u32_e32 v75, v75, v78
	v_lshlrev_b32_e32 v75, 9, v75
	v_and_b32_e32 v78, 7, v76
	v_lshl_add_u32 v75, v78, 3, v75
	v_and_b32_e32 v78, 3, v76
	v_lshlrev_b32_e32 v78, 4, v78
	v_sub_u32_e32 v75, v75, v78
	v_add_u32_e32 v70, v133, v74
	v_add_u32_e32 v71, v198, v74
	v_add_u32_e32 v72, v199, v75
	v_add_u32_e32 v73, v200, v75
	s_waitcnt vmcnt(6)
	v_cvt_pk_bf16_f32 v66, v102, v103
	v_cvt_pk_bf16_f32 v67, v104, v105
	s_waitcnt vmcnt(6)
	v_cvt_pk_bf16_f32 v68, v98, v99
	v_cvt_pk_bf16_f32 v69, v100, v101
	ds_write_b64 v70, v[66:67]
	ds_write_b64 v70, v[68:69] offset:128
	s_waitcnt vmcnt(4)
	v_cvt_pk_bf16_f32 v66, v110, v111
	v_cvt_pk_bf16_f32 v67, v112, v113
	s_waitcnt vmcnt(4)
	v_cvt_pk_bf16_f32 v68, v106, v107
	v_cvt_pk_bf16_f32 v69, v108, v109
	ds_write_b64 v71, v[66:67]
	ds_write_b64 v71, v[68:69] offset:128
	s_waitcnt vmcnt(2)
	v_cvt_pk_bf16_f32 v66, v118, v119
	v_cvt_pk_bf16_f32 v67, v120, v121
	s_waitcnt vmcnt(2)
	v_cvt_pk_bf16_f32 v68, v114, v115
	v_cvt_pk_bf16_f32 v69, v116, v117
	s_cmp_eq_u32 s4, 0xffc00000
	ds_write_b64 v72, v[66:67] offset:32768
	ds_write_b64 v72, v[68:69] offset:33792
	s_waitcnt vmcnt(0)
	v_cvt_pk_bf16_f32 v66, v126, v127
	v_cvt_pk_bf16_f32 v67, v128, v129
	s_waitcnt vmcnt(0)
	v_cvt_pk_bf16_f32 v68, v122, v123
	v_cvt_pk_bf16_f32 v69, v124, v125
	ds_write_b64 v73, v[66:67] offset:32768
	ds_write_b64 v73, v[68:69] offset:33792

; __device__ __forceinline__ int crow(int r, int hi) { return (r & 3) + 8 * (r >> 2) + 4 * hi; }
; __device__ __forceinline__ void qkt(f32x16& p0, f32x16& p1, const char* Ks, const char* Qs, int r32, int hi) {
; #pragma unroll
;     for (int d0 = 0; d0 < 8; ++d0) { const int cb = (d0 * 16 + hi * 8) * 2;
;         const bf16x8 qv = *reinterpret_cast<const bf16x8*>(Qs + KSWZ(r32, cb));
;         const bf16x8 b0 = *reinterpret_cast<const bf16x8*>(Ks + KSWZ(r32, cb));
;         const bf16x8 b1 = *reinterpret_cast<const bf16x8*>(Ks + KSWZ(32 + r32, cb));
;         p0 = __builtin_amdgcn_mfma_f32_32x32x16_bf16(b0, qv, p0, 0, 0, 0);
;         p1 = __builtin_amdgcn_mfma_f32_32x32x16_bf16(b1, qv, p1, 0, 0, 0); }
; }
; template <int MODE, bool SAMPLE>
; __device__ __forceinline__ void attn_unit(const Params& p, char* lds, int b, int h, int qb) {
;     ...
;         __syncthreads();
;         if (wact && j <= jd && var < 2) {
;             const char* Kt = K_lds + buf * 16384; const int vb = vb0 + buf * 16384;
;     ...
;                 p0 = f32x16{}; p1 = f32x16{};
;                 qkt(p0, p1, Kt, Qs, r32, hi);
;                 if (j == jd) {
; #pragma unroll
;                     for (int r = 0; r < 16; ++r) { const int kp = j * 64 + crow(r, hi); if (kp >= qpos) p0[r] = -1e30f; if (kp + 32 >= qpos) p1[r] = -1e30f; } }
.LBB0_644:
	s_and_b64 vcc, exec, s[0:1]
	s_waitcnt lgkmcnt(0)
	s_barrier
	s_cbranch_vccnz .LBB0_638
	s_setprio 2
	ds_read_b128 v[66:69], v202
	ds_read_b128 v[86:89], v202 offset:8192
	v_add_u32_e32 v70, s8, v182
	ds_read_b128 v[82:85], v70
	ds_read_b128 v[216:219], v203
	v_add_u32_e32 v147, s8, v184
	ds_read_b128 v[220:223], v147
	v_add_u32_e32 v147, s8, v185
	s_cmp_lg_u32 s4, 0
	s_waitcnt lgkmcnt(2)
	v_mfma_f32_32x32x16_bf16 v[66:81], v[66:69], v[82:85], 0
	s_waitcnt lgkmcnt(0)
	v_mfma_f32_32x32x16_bf16 v[66:81], v[216:219], v[220:223], v[66:81]
	ds_read_b128 v[216:219], v203 offset:8192
	v_mfma_f32_32x32x16_bf16 v[82:97], v[86:89], v[82:85], 0
	s_waitcnt lgkmcnt(0)
	v_mfma_f32_32x32x16_bf16 v[82:97], v[216:219], v[220:223], v[82:97]
	ds_read_b128 v[216:219], v204
	ds_read_b128 v[220:223], v147
	v_add_u32_e32 v147, s8, v186
	s_waitcnt lgkmcnt(0)
	v_mfma_f32_32x32x16_bf16 v[66:81], v[216:219], v[220:223], v[66:81]
	ds_read_b128 v[216:219], v204 offset:8192
	s_waitcnt lgkmcnt(0)
	v_mfma_f32_32x32x16_bf16 v[82:97], v[216:219], v[220:223], v[82:97]
	ds_read_b128 v[216:219], v205
	ds_read_b128 v[220:223], v147
	v_add_u32_e32 v147, s8, v187
	s_waitcnt lgkmcnt(0)
	v_mfma_f32_32x32x16_bf16 v[66:81], v[216:219], v[220:223], v[66:81]
	ds_read_b128 v[216:219], v205 offset:8192
	s_waitcnt lgkmcnt(0)
	v_mfma_f32_32x32x16_bf16 v[82:97], v[216:219], v[220:223], v[82:97]
	ds_read_b128 v[216:219], v206
	ds_read_b128 v[220:223], v147
	v_add_u32_e32 v147, s8, v188
	s_waitcnt lgkmcnt(0)
	v_mfma_f32_32x32x16_bf16 v[66:81], v[216:219], v[220:223], v[66:81]
	ds_read_b128 v[216:219], v206 offset:8192
	s_waitcnt lgkmcnt(0)
	v_mfma_f32_32x32x16_bf16 v[82:97], v[216:219], v[220:223], v[82:97]
	ds_read_b128 v[216:219], v207
	ds_read_b128 v[220:223], v147
	v_add_u32_e32 v147, s8, v189
	s_waitcnt lgkmcnt(0)
	v_mfma_f32_32x32x16_bf16 v[66:81], v[216:219], v[220:223], v[66:81]
	ds_read_b128 v[216:219], v207 offset:8192
	s_waitcnt lgkmcnt(0)
	v_mfma_f32_32x32x16_bf16 v[82:97], v[216:219], v[220:223], v[82:97]
	ds_read_b128 v[216:219], v208
	ds_read_b128 v[220:223], v147
	v_add_u32_e32 v147, s8, v190
	s_waitcnt lgkmcnt(0)
	v_mfma_f32_32x32x16_bf16 v[66:81], v[216:219], v[220:223], v[66:81]
	ds_read_b128 v[216:219], v208 offset:8192
	s_waitcnt lgkmcnt(0)
	v_mfma_f32_32x32x16_bf16 v[82:97], v[216:219], v[220:223], v[82:97]
	ds_read_b128 v[216:219], v209
	ds_read_b128 v[220:223], v147
	s_waitcnt lgkmcnt(0)
	v_mfma_f32_32x32x16_bf16 v[66:81], v[216:219], v[220:223], v[66:81]
	ds_read_b128 v[216:219], v209 offset:8192
	s_waitcnt lgkmcnt(0)
	v_mfma_f32_32x32x16_bf16 v[82:97], v[216:219], v[220:223], v[82:97]
	s_cbranch_scc1 .LBB0_637
	s_nop 7
	v_mov_b32_e32 v74, 0xf149f2ca
	s_or_b64 vcc, s[52:53], s[24:25]
	v_cndmask_b32_e64 v73, v74, v73, s[78:79]
	v_cndmask_b32_e32 v66, v74, v66, vcc
	v_cndmask_b32_e64 v67, v74, v67, s[52:53]
	v_cndmask_b32_e64 v68, v74, v68, s[84:85]
	v_cndmask_b32_e64 v69, v74, v69, s[18:19]
	v_cndmask_b32_e64 v70, v74, v70, s[20:21]
	v_cndmask_b32_e64 v71, v74, v71, s[56:57]
	v_cndmask_b32_e64 v72, v74, v72, s[80:81]
	v_mov_b32_e32 v75, v74
	v_mov_b32_e32 v76, v74
	v_mov_b32_e32 v77, v74
	v_mov_b32_e32 v78, v74
	v_mov_b32_e32 v79, v74
	v_mov_b32_e32 v80, v74
	v_mov_b32_e32 v81, v74
	v_mov_b32_e32 v82, v74
	v_mov_b32_e32 v83, v74
	v_mov_b32_e32 v84, v74
	v_mov_b32_e32 v85, v74
	v_mov_b32_e32 v86, v74
	v_mov_b32_e32 v87, v74
	v_mov_b32_e32 v88, v74
	v_mov_b32_e32 v89, v74
	v_mov_b32_e32 v90, v74
	v_mov_b32_e32 v91, v74
	v_mov_b32_e32 v92, v74
	v_mov_b32_e32 v93, v74
	v_mov_b32_e32 v94, v74
	v_mov_b32_e32 v95, v74
	v_mov_b32_e32 v96, v74
	v_mov_b32_e32 v97, v74
	s_branch .LBB0_637

; template <int MODE, bool SAMPLE>
; __device__ __forceinline__ void attn_unit(const Params& p, char* lds, int b, int h, int qb) {
;     ...
;         WRITET(buf, stg2[NS == 2 ? par : 0]);
;         if (j >= NS) LOADT(j - NS, stg2[NS == 2 ? par : 0]);
;         __syncthreads();
;         if (wact && j <= jd && var < 2) {
;             const char* Kt = K_lds + buf * 16384; const int vb = vb0 + buf * 16384;
;             f32x16 p0, p1; bf16x8 pa0, pa1, pa2, pa3;
;             if (MODE == 0) {
;                 const float* bt = biasL + j * 64 + 4 * hi;
; #pragma unroll
;                 for (int g = 0; g < 4; ++g) { const f32x4 a = *(const f32x4*)(bt + 8 * g), c = *(const f32x4*)(bt + 32 + 8 * g);
; #pragma unroll
;                     for (int i = 0; i < 4; ++i) { p0[4 * g + i] = a[i]; p1[4 * g + i] = c[i]; } }
;                 qkt(p0, p1, Kt, Qs, r32, hi);
.LBB0_843:
	s_setprio 0
	s_mov_b32 s0, 0xfffe0000
	s_add_i32 s55, s55, -1
	s_addk_i32 s52, 0xff80
	s_addk_i32 s96, 0xfe00
	s_mov_b32 s1, -1
	s_cmpk_eq_i32 s96, 0xee00
	v_lshl_add_u64 v[168:169], v[168:169], 0, s[0:1]
	s_cbranch_scc1 .LBB0_859
.LBB0_844:
	v_cndmask_b32_e64 v66, 0, 1, s[74:75]
	s_cmp_lt_u32 s55, 8
	v_lshlrev_b32_e32 v0, 2, v150
	v_lshlrev_b32_e32 v162, 2, v152
	v_cmp_ne_u32_e64 s[0:1], 1, v66
	s_cbranch_scc0 .Lfsr_first_f2
	v_and_b32_e32 v76, 15, v183
	v_bfe_u32 v77, v183, 4, 3
	v_xor_b32_e32 v78, v76, v77
	v_lshrrev_b32_e32 v74, 1, v76
	v_xor_b32_e32 v74, v74, v77
	v_sub_u32_e32 v74, v74, v78
	v_and_b32_e32 v78, 1, v76
	v_lshlrev_b32_e32 v74, 4, v74
	v_lshl_add_u32 v74, v78, 3, v74
	v_lshrrev_b32_e32 v75, 3, v76
	v_lshrrev_b32_e32 v78, 2, v76
	v_sub_u32_e32 v75, v75, v78
	v_lshlrev_b32_e32 v75, 9, v75
	v_and_b32_e32 v78, 7, v76
	v_lshl_add_u32 v75, v78, 3, v75
	v_and_b32_e32 v78, 3, v76
	v_lshlrev_b32_e32 v78, 4, v78
	v_sub_u32_e32 v75, v75, v78
	v_add_u32_e32 v70, v198, v74
	v_add_u32_e32 v71, v199, v74
	v_add_u32_e32 v72, v200, v75
	v_add_u32_e32 v73, v201, v75
	s_waitcnt vmcnt(6)
	v_cvt_pk_bf16_f32 v66, v102, v103
	v_cvt_pk_bf16_f32 v67, v104, v105
	v_cvt_pk_bf16_f32 v68, v98, v99
	v_cvt_pk_bf16_f32 v69, v100, v101
	ds_write_b64 v70, v[66:67] offset:16384
	ds_write_b64 v70, v[68:69] offset:16512
	s_waitcnt vmcnt(4)
	v_cvt_pk_bf16_f32 v66, v110, v111
	v_cvt_pk_bf16_f32 v67, v112, v113
	v_cvt_pk_bf16_f32 v68, v106, v107
	v_cvt_pk_bf16_f32 v69, v108, v109
	ds_write_b64 v71, v[66:67] offset:16384
	ds_write_b64 v71, v[68:69] offset:16512
	s_waitcnt vmcnt(2)
	v_cvt_pk_bf16_f32 v66, v122, v123
	v_cvt_pk_bf16_f32 v67, v124, v125
	v_cvt_pk_bf16_f32 v68, v114, v115
	v_cvt_pk_bf16_f32 v69, v116, v117
	ds_write_b64 v72, v[66:67] offset:49152
	ds_write_b64 v72, v[68:69] offset:50176
	s_waitcnt vmcnt(0)
	v_cvt_pk_bf16_f32 v66, v126, v127
	v_cvt_pk_bf16_f32 v67, v128, v129
	v_cvt_pk_bf16_f32 v68, v118, v119
	v_cvt_pk_bf16_f32 v69, v120, v121
	ds_write_b64 v73, v[66:67] offset:49152
	ds_write_b64 v73, v[68:69] offset:50176
	v_or_b32_e32 v67, s61, v169
	v_or_b32_e32 v66, s9, v168
	v_readlane_b32 s36, v253, 16
	v_lshlrev_b64 v[66:67], 2, v[66:67]
	v_and_b32_e32 v72, 15, v183
	v_lshlrev_b32_e32 v72, 4, v72
	v_sub_u32_e32 v66, v66, v72
	v_readlane_b32 s40, v253, 20
	v_readlane_b32 s41, v253, 21
	v_readlane_b32 s42, v253, 22
	v_readlane_b32 s43, v253, 23
	v_lshl_add_u64 v[68:69], s[40:41], 0, v[66:67]
	v_mov_b32_e32 v163, v1
	v_lshl_add_u64 v[70:71], v[68:69], 0, v[0:1]
	v_lshl_add_u64 v[68:69], v[68:69], 0, v[162:163]
	v_lshl_add_u64 v[66:67], s[42:43], 0, v[66:67]
	global_load_dwordx4 v[98:101], v[70:71], off offset:256 nt
	global_load_dwordx4 v[102:105], v[70:71], off nt
	global_load_dwordx4 v[106:109], v[68:69], off offset:256 nt
	global_load_dwordx4 v[110:113], v[68:69], off nt
	v_lshl_add_u64 v[68:69], v[66:67], 0, v[0:1]
	v_lshl_add_u64 v[66:67], v[66:67], 0, v[162:163]
	global_load_dwordx4 v[114:117], v[68:69], off offset:256 nt
	global_load_dwordx4 v[122:125], v[68:69], off nt
	global_load_dwordx4 v[118:121], v[66:67], off offset:256 nt
	global_load_dwordx4 v[126:129], v[66:67], off nt
	s_and_b64 vcc, exec, s[0:1]
	v_readlane_b32 s37, v253, 17
	v_readlane_b32 s38, v253, 18
	v_readlane_b32 s39, v253, 19
	v_readlane_b32 s44, v253, 24
	v_readlane_b32 s45, v253, 25
	v_readlane_b32 s46, v253, 26
	v_readlane_b32 s47, v253, 27
	v_readlane_b32 s48, v253, 28
	v_readlane_b32 s49, v253, 29
	v_readlane_b32 s50, v253, 30
	v_readlane_b32 s51, v253, 31
	s_waitcnt lgkmcnt(0)
	s_barrier
	s_cbranch_vccnz .LBB0_851
	s_setprio 2
	v_add_u32_e32 v78, s96, v135
	v_add_u32_e32 v66, 0x11100, v78
	v_add_u32_e32 v67, 0x11180, v78
	v_add_u32_e32 v70, 0x11120, v78
	v_add_u32_e32 v74, 0x11140, v78
	ds_read_b128 v[82:85], v66
	ds_read_b128 v[66:69], v67
	ds_read_b128 v[86:89], v70
	ds_read_b128 v[90:93], v74
	v_add_u32_e32 v70, 0x111a0, v78
	v_add_u32_e32 v74, 0x111c0, v78
	v_add_u32_e32 v79, 0x11160, v78
	v_add_u32_e32 v78, 0x111e0, v78
	ds_read_b128 v[94:97], v79
	ds_read_b128 v[78:81], v78
	ds_read_b128 v[70:73], v70
	ds_read_b128 v[74:77], v74
	v_add_u32_e32 v163, s33, v181
	ds_read_b128 v[204:207], v163
	ds_read_b128 v[212:215], v181 offset:16384
	ds_read_b128 v[216:219], v181 offset:24576
	v_add_u32_e32 v163, s33, v182
	ds_read_b128 v[234:237], v163
	ds_read_b128 v[238:241], v182 offset:16384
	ds_read_b128 v[242:245], v182 offset:24576
	s_waitcnt lgkmcnt(4)
	v_mfma_f32_32x32x16_bf16 v[82:97], v[212:215], v[204:207], v[82:97]
	s_waitcnt lgkmcnt(3)
	v_mfma_f32_32x32x16_bf16 v[66:81], v[216:219], v[204:207], v[66:81]
	v_add_u32_e32 v163, s33, v184
	ds_read_b128 v[204:207], v163
	ds_read_b128 v[212:215], v184 offset:16384
	ds_read_b128 v[216:219], v184 offset:24576
	s_waitcnt lgkmcnt(4)
	v_mfma_f32_32x32x16_bf16 v[82:97], v[238:241], v[234:237], v[82:97]
	s_waitcnt lgkmcnt(3)
	v_mfma_f32_32x32x16_bf16 v[66:81], v[242:245], v[234:237], v[66:81]
	v_add_u32_e32 v163, s33, v185
	ds_read_b128 v[234:237], v163
	ds_read_b128 v[238:241], v185 offset:16384
	ds_read_b128 v[242:245], v185 offset:24576
	s_waitcnt lgkmcnt(4)
	v_mfma_f32_32x32x16_bf16 v[82:97], v[212:215], v[204:207], v[82:97]
	s_waitcnt lgkmcnt(3)
	v_mfma_f32_32x32x16_bf16 v[66:81], v[216:219], v[204:207], v[66:81]
	v_add_u32_e32 v163, s33, v186
	ds_read_b128 v[204:207], v163
	ds_read_b128 v[212:215], v186 offset:16384
	ds_read_b128 v[216:219], v186 offset:24576
	s_waitcnt lgkmcnt(4)
	v_mfma_f32_32x32x16_bf16 v[82:97], v[238:241], v[234:237], v[82:97]
	s_waitcnt lgkmcnt(3)
	v_mfma_f32_32x32x16_bf16 v[66:81], v[242:245], v[234:237], v[66:81]
	v_add_u32_e32 v163, s33, v187
	ds_read_b128 v[234:237], v163
	ds_read_b128 v[238:241], v187 offset:16384
	ds_read_b128 v[242:245], v187 offset:24576
	s_waitcnt lgkmcnt(4)
; __device__ __forceinline__ int crow(int r, int hi) { return (r & 3) + 8 * (r >> 2) + 4 * hi; }
; template <int MODE, bool SAMPLE>
; __device__ __forceinline__ void attn_unit(const Params& p, char* lds, int b, int h, int qb) {
;     ...
;                 qkt(p0, p1, Kt, Qs, r32, hi);
;                 if (j == jd) {
; #pragma unroll
;                     for (int r = 0; r < 16; ++r) { const int kp = j * 64 + crow(r, hi); if (kp > qpos) p0[r] = -1e30f; if (kp + 32 > qpos) p1[r] = -1e30f; } }
;                 float pmax = p0[0];
; #pragma unroll
;                 for (int r = 1; r < 16; ++r) pmax = fmaxf(pmax, p0[r]);
; #pragma unroll
;                 for (int r = 0; r < 16; ++r) pmax = fmaxf(pmax, p1[r]);
;                 { auto rr = __builtin_amdgcn_permlane32_swap(__float_as_uint(pmax), __float_as_uint(pmax), false, false); pmax = fmaxf(__uint_as_float(rr[0]), __uint_as_float(rr[1])); }
;                 float alpha = 1.f;
;                 if (!__all(pmax - m_reg <= 8.f)) { const float mn = fmaxf(m_reg, pmax); alpha = __builtin_amdgcn_exp2f(m_reg - mn); m_reg = mn; }
;                 float ps = 0.f;
; #pragma unroll
;                 for (int r = 0; r < 16; ++r) { p0[r] = __builtin_amdgcn_exp2f(p0[r] - m_reg); p1[r] = __builtin_amdgcn_exp2f(p1[r] - m_reg); ps += p0[r] + p1[r]; }
;                 { auto rr = __builtin_amdgcn_permlane32_swap(__float_as_uint(ps), __float_as_uint(ps), false, false); ps = __uint_as_float(rr[0]) + __uint_as_float(rr[1]); }
;                 l_reg = l_reg * alpha + ps;
;                 if (__any(alpha < 1.f)) { if (hi == 0) wsc[r32] = alpha; asm volatile("s_waitcnt lgkmcnt(0)" ::: "memory");
; #pragma unroll
;                     for (int d = 0; d < 4; ++d)
; #pragma unroll
;                         for (int r = 0; r < 16; ++r) o[d][r] *= wsc[crow(r, hi)]; }
	v_mfma_f32_32x32x16_bf16 v[82:97], v[212:215], v[204:207], v[82:97]
	s_waitcnt lgkmcnt(3)
	v_mfma_f32_32x32x16_bf16 v[66:81], v[216:219], v[204:207], v[66:81]
	v_add_u32_e32 v163, s33, v188
	ds_read_b128 v[204:207], v163
	ds_read_b128 v[212:215], v188 offset:16384
	ds_read_b128 v[216:219], v188 offset:24576
	s_waitcnt lgkmcnt(4)
	v_mfma_f32_32x32x16_bf16 v[82:97], v[238:241], v[234:237], v[82:97]
	s_waitcnt lgkmcnt(3)
	v_mfma_f32_32x32x16_bf16 v[66:81], v[242:245], v[234:237], v[66:81]
	v_add_u32_e32 v163, s33, v189
	ds_read_b128 v[234:237], v163
	ds_read_b128 v[238:241], v189 offset:16384
	ds_read_b128 v[242:245], v189 offset:24576
	s_waitcnt lgkmcnt(4)
	v_mfma_f32_32x32x16_bf16 v[82:97], v[212:215], v[204:207], v[82:97]
	s_waitcnt lgkmcnt(3)
	v_mfma_f32_32x32x16_bf16 v[66:81], v[216:219], v[204:207], v[66:81]
	s_waitcnt lgkmcnt(1)
	v_mfma_f32_32x32x16_bf16 v[82:97], v[238:241], v[234:237], v[82:97]
	s_waitcnt lgkmcnt(0)
	v_mfma_f32_32x32x16_bf16 v[66:81], v[242:245], v[234:237], v[66:81]
	s_nop 1
	s_nop 9
	v_max_f32_e32 v163, v83, v83
	v_max_f32_e32 v203, v82, v82
	v_max_f32_e32 v163, v203, v163
	v_max3_f32 v163, v163, v84, v85
	v_max3_f32 v163, v163, v86, v87
	v_max3_f32 v163, v163, v88, v89
	v_max3_f32 v163, v163, v90, v91
	v_max3_f32 v163, v163, v92, v93
	v_max3_f32 v163, v163, v94, v95
	v_max3_f32 v163, v163, v96, v97
	v_max3_f32 v163, v163, v66, v67
	v_max3_f32 v163, v163, v68, v69
	v_max3_f32 v163, v163, v70, v71
	v_max3_f32 v163, v163, v72, v73
	v_max3_f32 v163, v163, v74, v75
	v_max3_f32 v163, v163, v76, v77
	v_max3_f32 v163, v163, v78, v79
	v_max3_f32 v163, v163, v80, v81
	v_mov_b32_e32 v203, v163
	s_nop 1
	v_permlane32_swap_b32_e32 v163, v203
	v_max_f32_e32 v203, v203, v203
	v_max_f32_e32 v163, v163, v163
	v_max_f32_e32 v163, v163, v203
	v_sub_f32_e32 v203, v163, v161
	v_cmp_ge_f32_e32 vcc, s82, v203
	s_cmp_eq_u64 vcc, exec
	v_max_f32_e32 v203, v161, v161
	s_cselect_b64 vcc, -1, 0
	v_max_f32_e32 v163, v203, v163
	v_sub_f32_e32 v203, v161, v163
	v_cndmask_b32_e32 v161, v163, v161, vcc
	v_sub_f32_e32 v82, v82, v161
	v_sub_f32_e32 v66, v66, v161
	v_exp_f32_e32 v163, v82
	v_exp_f32_e32 v82, v66
	v_exp_f32_e32 v204, v203
	v_sub_f32_e32 v67, v67, v161
	v_sub_f32_e32 v68, v68, v161
	v_add_f32_e32 v66, v163, v82
	v_add_f32_e32 v203, 0, v66
	v_sub_f32_e32 v66, v83, v161
	v_exp_f32_e32 v66, v66
	v_exp_f32_e32 v83, v67
	v_sub_f32_e32 v69, v69, v161
	v_sub_f32_e32 v70, v70, v161
	v_exp_f32_e32 v70, v70
	v_add_f32_e32 v67, v66, v83
	v_add_f32_e32 v203, v67, v203
	v_sub_f32_e32 v67, v84, v161
	v_exp_f32_e32 v67, v67
	v_exp_f32_e32 v84, v68
	v_sub_f32_e32 v71, v71, v161
	v_exp_f32_e32 v71, v71
	v_sub_f32_e32 v72, v72, v161
	v_add_f32_e32 v68, v67, v84
	v_add_f32_e32 v203, v68, v203
	v_sub_f32_e32 v68, v85, v161
	v_exp_f32_e32 v68, v68
	v_exp_f32_e32 v85, v69
	v_exp_f32_e32 v72, v72
	v_sub_f32_e32 v73, v73, v161
	v_exp_f32_e32 v73, v73
	v_add_f32_e32 v69, v68, v85
	v_add_f32_e32 v203, v69, v203
	v_sub_f32_e32 v69, v86, v161
	v_exp_f32_e32 v69, v69
	v_sub_f32_e32 v74, v74, v161
	v_exp_f32_e32 v74, v74
	v_sub_f32_e32 v75, v75, v161
	v_add_f32_e32 v86, v69, v70
	v_add_f32_e32 v203, v86, v203
	v_sub_f32_e32 v86, v87, v161
	v_exp_f32_e32 v86, v86
	v_exp_f32_e32 v75, v75
	v_sub_f32_e32 v76, v76, v161
	v_exp_f32_e32 v76, v76
	v_add_f32_e32 v87, v86, v71
	v_add_f32_e32 v203, v87, v203
	v_sub_f32_e32 v87, v88, v161
	v_exp_f32_e32 v87, v87
	v_sub_f32_e32 v77, v77, v161
	v_exp_f32_e32 v77, v77
	v_sub_f32_e32 v78, v78, v161
	v_add_f32_e32 v88, v87, v72
	v_add_f32_e32 v203, v88, v203
	v_sub_f32_e32 v88, v89, v161
	v_exp_f32_e32 v88, v88
	v_exp_f32_e32 v78, v78
	v_sub_f32_e32 v79, v79, v161
	v_exp_f32_e32 v79, v79
	v_add_f32_e32 v89, v88, v73
	v_add_f32_e32 v203, v89, v203
	v_sub_f32_e32 v89, v90, v161
	v_exp_f32_e32 v89, v89
	v_sub_f32_e32 v80, v80, v161
	v_exp_f32_e32 v80, v80
	v_sub_f32_e32 v81, v81, v161
	v_add_f32_e32 v90, v89, v74
	v_add_f32_e32 v203, v90, v203
	v_sub_f32_e32 v90, v91, v161
	v_exp_f32_e32 v90, v90
	v_exp_f32_e32 v81, v81
	v_add_f32_e32 v91, v90, v75
	v_add_f32_e32 v203, v91, v203
	v_sub_f32_e32 v91, v92, v161
	v_exp_f32_e32 v91, v91
	s_nop 0
	v_add_f32_e32 v92, v91, v76
	v_add_f32_e32 v203, v92, v203
	v_sub_f32_e32 v92, v93, v161
	v_exp_f32_e32 v92, v92
	s_nop 0
	v_add_f32_e32 v93, v92, v77
	v_add_f32_e32 v203, v93, v203
	v_sub_f32_e32 v93, v94, v161
	v_exp_f32_e32 v93, v93
	s_nop 0
	v_add_f32_e32 v94, v93, v78
	v_add_f32_e32 v203, v94, v203
	v_sub_f32_e32 v94, v95, v161
	v_exp_f32_e32 v94, v94
	s_nop 0
	v_add_f32_e32 v95, v94, v79
	v_add_f32_e32 v203, v95, v203
	v_sub_f32_e32 v95, v96, v161
	v_exp_f32_e32 v95, v95
	s_nop 0
	v_add_f32_e32 v96, v95, v80
	v_add_f32_e32 v203, v96, v203
	v_sub_f32_e32 v96, v97, v161
	v_exp_f32_e32 v96, v96
	s_nop 0
	v_add_f32_e32 v97, v96, v81
	v_add_f32_e32 v203, v97, v203
	v_cndmask_b32_e64 v97, v204, 1.0, vcc
	v_mov_b32_e32 v204, v203
	s_nop 1
	v_permlane32_swap_b32_e32 v203, v204
	v_cmp_gt_f32_e32 vcc, 1.0, v97
	s_cbranch_vccz .LBB0_850
	s_and_saveexec_b64 s[2:3], s[12:13]
	ds_write_b32 v147, v97
	s_or_b64 exec, exec, s[2:3]
	s_waitcnt lgkmcnt(0)
	ds_read_b128 v[206:209], v149 offset:96
	ds_read_b128 v[212:215], v149 offset:64
	ds_read_b128 v[216:219], v149 offset:32
	ds_read_b128 v[220:223], v149
	s_waitcnt lgkmcnt(3)
	v_pk_mul_f32 v[64:65], v[64:65], v[208:209]
	s_waitcnt lgkmcnt(2)
	v_pk_mul_f32 v[60:61], v[60:61], v[214:215]
	s_waitcnt lgkmcnt(1)
	v_pk_mul_f32 v[56:57], v[56:57], v[218:219]
	s_waitcnt lgkmcnt(0)
	v_pk_mul_f32 v[52:53], v[52:53], v[222:223]
	v_pk_mul_f32 v[62:63], v[62:63], v[206:207]
	v_pk_mul_f32 v[58:59], v[58:59], v[212:213]
	v_pk_mul_f32 v[54:55], v[54:55], v[216:217]
	v_pk_mul_f32 v[50:51], v[50:51], v[220:221]
	v_pk_mul_f32 v[48:49], v[48:49], v[208:209]
	v_pk_mul_f32 v[44:45], v[44:45], v[214:215]
	v_pk_mul_f32 v[40:41], v[40:41], v[218:219]
	v_pk_mul_f32 v[36:37], v[36:37], v[222:223]
	v_pk_mul_f32 v[46:47], v[46:47], v[206:207]
	v_pk_mul_f32 v[42:43], v[42:43], v[212:213]
	v_pk_mul_f32 v[38:39], v[38:39], v[216:217]
	v_pk_mul_f32 v[34:35], v[34:35], v[220:221]
	v_pk_mul_f32 v[32:33], v[32:33], v[208:209]
	v_pk_mul_f32 v[28:29], v[28:29], v[214:215]
	v_pk_mul_f32 v[24:25], v[24:25], v[218:219]
	v_pk_mul_f32 v[20:21], v[20:21], v[222:223]
	v_pk_mul_f32 v[30:31], v[30:31], v[206:207]
	v_pk_mul_f32 v[26:27], v[26:27], v[212:213]
	v_pk_mul_f32 v[22:23], v[22:23], v[216:217]
	v_pk_mul_f32 v[18:19], v[18:19], v[220:221]
	v_pk_mul_f32 v[16:17], v[16:17], v[208:209]
	v_pk_mul_f32 v[12:13], v[12:13], v[214:215]
	v_pk_mul_f32 v[8:9], v[8:9], v[218:219]
	v_pk_mul_f32 v[4:5], v[4:5], v[222:223]
	v_pk_mul_f32 v[14:15], v[14:15], v[206:207]
	v_pk_mul_f32 v[10:11], v[10:11], v[212:213]
	v_pk_mul_f32 v[6:7], v[6:7], v[216:217]
	v_pk_mul_f32 v[2:3], v[2:3], v[220:221]

; template <int MODE, bool SAMPLE>
; __device__ __forceinline__ void attn_unit(const Params& p, char* lds, int b, int h, int qb) {
;     ...
;         WRITET(buf, stg2[NS == 2 ? par : 0]);
.LBB0_851:
	s_setprio 0
	v_and_b32_e32 v76, 15, v183
	v_bfe_u32 v77, v183, 4, 3
	v_xor_b32_e32 v78, v76, v77
	v_lshrrev_b32_e32 v74, 1, v76
	v_xor_b32_e32 v74, v74, v77
	v_sub_u32_e32 v74, v74, v78
	v_and_b32_e32 v78, 1, v76
	v_lshlrev_b32_e32 v74, 4, v74
	v_lshl_add_u32 v74, v78, 3, v74
	v_lshrrev_b32_e32 v75, 3, v76
	v_lshrrev_b32_e32 v78, 2, v76
	v_sub_u32_e32 v75, v75, v78
	v_lshlrev_b32_e32 v75, 9, v75
	v_and_b32_e32 v78, 7, v76
	v_lshl_add_u32 v75, v78, 3, v75
	v_and_b32_e32 v78, 3, v76
	v_lshlrev_b32_e32 v78, 4, v78
	v_sub_u32_e32 v75, v75, v78
	v_add_u32_e32 v70, v198, v74
	v_add_u32_e32 v71, v199, v74
	v_add_u32_e32 v72, v200, v75
	v_add_u32_e32 v73, v201, v75
	s_waitcnt vmcnt(6)
	v_cvt_pk_bf16_f32 v66, v102, v103
	v_cvt_pk_bf16_f32 v67, v104, v105
	v_cvt_pk_bf16_f32 v68, v98, v99
	v_cvt_pk_bf16_f32 v69, v100, v101
	ds_write_b64 v70, v[66:67]
	ds_write_b64 v70, v[68:69] offset:128
	s_waitcnt vmcnt(4)
	v_cvt_pk_bf16_f32 v66, v110, v111
	v_cvt_pk_bf16_f32 v67, v112, v113
	v_cvt_pk_bf16_f32 v68, v106, v107
	v_cvt_pk_bf16_f32 v69, v108, v109
	ds_write_b64 v71, v[66:67]
	ds_write_b64 v71, v[68:69] offset:128
	s_waitcnt vmcnt(2)
	v_cvt_pk_bf16_f32 v66, v122, v123
	v_cvt_pk_bf16_f32 v67, v124, v125
	v_cvt_pk_bf16_f32 v68, v114, v115
	v_cvt_pk_bf16_f32 v69, v116, v117
	s_cmpk_eq_i32 s96, 0xf000
	ds_write_b64 v72, v[66:67] offset:32768
	ds_write_b64 v72, v[68:69] offset:33792
	s_waitcnt vmcnt(0)
	v_cvt_pk_bf16_f32 v66, v126, v127
	v_cvt_pk_bf16_f32 v67, v128, v129
	v_cvt_pk_bf16_f32 v68, v118, v119
	v_cvt_pk_bf16_f32 v69, v120, v121
	ds_write_b64 v73, v[66:67] offset:32768
	ds_write_b64 v73, v[68:69] offset:33792

; __device__ __forceinline__ int crow(int r, int hi) { return (r & 3) + 8 * (r >> 2) + 4 * hi; }
; template <int MODE, bool SAMPLE>
; __device__ __forceinline__ void attn_unit(const Params& p, char* lds, int b, int h, int qb) {
;     ...
;         __syncthreads();
;         if (wact && j <= jd && var < 2) {
;             const char* Kt = K_lds + buf * 16384; const int vb = vb0 + buf * 16384;
;             f32x16 p0, p1; bf16x8 pa0, pa1, pa2, pa3;
;             if (MODE == 0) {
;                 const float* bt = biasL + j * 64 + 4 * hi;
; #pragma unroll
;                 for (int g = 0; g < 4; ++g) { const f32x4 a = *(const f32x4*)(bt + 8 * g), c = *(const f32x4*)(bt + 32 + 8 * g);
; #pragma unroll
;                     for (int i = 0; i < 4; ++i) { p0[4 * g + i] = a[i]; p1[4 * g + i] = c[i]; } }
;                 qkt(p0, p1, Kt, Qs, r32, hi);
;                 if (j == jd) {
; #pragma unroll
;                     for (int r = 0; r < 16; ++r) { const int kp = j * 64 + crow(r, hi); if (kp > qpos) p0[r] = -1e30f; if (kp + 32 > qpos) p1[r] = -1e30f; } }
.LBB0_853:
	s_and_b64 vcc, exec, s[0:1]
	v_add_u32_e32 v203, 0, v181
	v_add_u32_e32 v204, 0, v182
	v_add_u32_e32 v205, 0, v184
	v_add_u32_e32 v206, 0, v185
	v_add_u32_e32 v207, 0, v186
	v_add_u32_e32 v208, 0, v187
	v_add_u32_e32 v209, 0, v188
	v_add_u32_e32 v210, 0, v189
	s_waitcnt lgkmcnt(0)
	s_barrier
	s_cbranch_vccnz .LBB0_843
	s_setprio 2
	v_add_u32_e32 v94, s96, v135
	v_add_u32_e32 v66, 0x11000, v94
	v_add_u32_e32 v70, 0x11080, v94
	ds_read_b128 v[66:69], v66
	ds_read_b128 v[82:85], v70
	v_add_u32_e32 v70, 0x11020, v94
	v_add_u32_e32 v74, 0x11040, v94
	v_add_u32_e32 v78, 0x11060, v94
	ds_read_b128 v[70:73], v70
	ds_read_b128 v[74:77], v74
	ds_read_b128 v[78:81], v78
	v_add_u32_e32 v86, 0x110a0, v94
	v_add_u32_e32 v95, 0x110c0, v94
	v_add_u32_e32 v94, 0x110e0, v94
	ds_read_b128 v[86:89], v86
	ds_read_b128 v[90:93], v95
	ds_read_b128 v[94:97], v94
	s_cmp_lg_u32 s96, 0
	v_add_u32_e32 v163, s33, v181
	ds_read_b128 v[216:219], v163
	ds_read_b128 v[212:215], v203
	ds_read_b128 v[246:249], v203 offset:8192
	v_add_u32_e32 v163, s33, v182
	ds_read_b128 v[234:237], v163
	ds_read_b128 v[238:241], v204
	ds_read_b128 v[242:245], v204 offset:8192
	s_waitcnt lgkmcnt(4)
	v_mfma_f32_32x32x16_bf16 v[66:81], v[212:215], v[216:219], v[66:81]
	s_waitcnt lgkmcnt(3)
	v_mfma_f32_32x32x16_bf16 v[82:97], v[246:249], v[216:219], v[82:97]
	v_add_u32_e32 v163, s33, v184
	ds_read_b128 v[216:219], v163
	ds_read_b128 v[212:215], v205
	ds_read_b128 v[246:249], v205 offset:8192
	s_waitcnt lgkmcnt(4)
	v_mfma_f32_32x32x16_bf16 v[66:81], v[238:241], v[234:237], v[66:81]
	s_waitcnt lgkmcnt(3)
	v_mfma_f32_32x32x16_bf16 v[82:97], v[242:245], v[234:237], v[82:97]
	v_add_u32_e32 v163, s33, v185
	ds_read_b128 v[234:237], v163
	ds_read_b128 v[238:241], v206
	ds_read_b128 v[242:245], v206 offset:8192
	s_waitcnt lgkmcnt(4)
	v_mfma_f32_32x32x16_bf16 v[66:81], v[212:215], v[216:219], v[66:81]
	s_waitcnt lgkmcnt(3)
	v_mfma_f32_32x32x16_bf16 v[82:97], v[246:249], v[216:219], v[82:97]
	v_add_u32_e32 v163, s33, v186
	ds_read_b128 v[216:219], v163
	ds_read_b128 v[212:215], v207
	ds_read_b128 v[246:249], v207 offset:8192
	s_waitcnt lgkmcnt(4)
	v_mfma_f32_32x32x16_bf16 v[66:81], v[238:241], v[234:237], v[66:81]
	s_waitcnt lgkmcnt(3)
	v_mfma_f32_32x32x16_bf16 v[82:97], v[242:245], v[234:237], v[82:97]
	v_add_u32_e32 v163, s33, v187
	ds_read_b128 v[234:237], v163
	ds_read_b128 v[238:241], v208
	ds_read_b128 v[242:245], v208 offset:8192
	s_waitcnt lgkmcnt(4)
	v_mfma_f32_32x32x16_bf16 v[66:81], v[212:215], v[216:219], v[66:81]
	s_waitcnt lgkmcnt(3)
	v_mfma_f32_32x32x16_bf16 v[82:97], v[246:249], v[216:219], v[82:97]
	v_add_u32_e32 v163, s33, v188
	ds_read_b128 v[216:219], v163
	ds_read_b128 v[212:215], v209
	ds_read_b128 v[246:249], v209 offset:8192
	s_waitcnt lgkmcnt(4)
	v_mfma_f32_32x32x16_bf16 v[66:81], v[238:241], v[234:237], v[66:81]
	s_waitcnt lgkmcnt(3)
	v_mfma_f32_32x32x16_bf16 v[82:97], v[242:245], v[234:237], v[82:97]
	v_add_u32_e32 v163, s33, v189
	ds_read_b128 v[234:237], v163
	ds_read_b128 v[238:241], v210
	ds_read_b128 v[242:245], v210 offset:8192
	s_waitcnt lgkmcnt(4)
	v_mfma_f32_32x32x16_bf16 v[66:81], v[212:215], v[216:219], v[66:81]
	s_waitcnt lgkmcnt(3)
	v_mfma_f32_32x32x16_bf16 v[82:97], v[246:249], v[216:219], v[82:97]
	s_waitcnt lgkmcnt(1)
	v_mfma_f32_32x32x16_bf16 v[66:81], v[238:241], v[234:237], v[66:81]
	s_waitcnt lgkmcnt(0)
	v_mfma_f32_32x32x16_bf16 v[82:97], v[242:245], v[234:237], v[82:97]
	s_nop 1
	s_cbranch_scc1 .LBB0_856
	s_nop 10
	v_mov_b32_e32 v82, 0xf149f2ca
	v_cndmask_b32_e64 v74, v66, v82, s[20:21]
	v_cndmask_b32_e64 v66, v74, v66, s[22:23]
	v_cndmask_b32_e64 v67, v82, v67, s[22:23]
	v_cndmask_b32_e64 v68, v68, v82, s[24:25]
	v_cndmask_b32_e64 v69, v69, v82, s[26:27]
	v_cndmask_b32_e64 v70, v70, v82, s[28:29]
	v_cndmask_b32_e64 v71, v71, v82, s[30:31]
	v_cndmask_b32_e64 v72, v72, v82, s[34:35]
	v_cndmask_b32_e64 v73, v73, v82, s[18:19]
	v_mov_b32_e32 v83, v82
	v_mov_b32_e32 v84, v82
	v_mov_b32_e32 v85, v82
	v_mov_b32_e32 v86, v82
	v_mov_b32_e32 v87, v82
	v_mov_b32_e32 v88, v82
	v_mov_b32_e32 v89, v82
	v_mov_b32_e32 v90, v82
	v_mov_b32_e32 v91, v82
	v_mov_b32_e32 v92, v82
	v_mov_b32_e32 v93, v82
	v_mov_b32_e32 v94, v82
	v_mov_b32_e32 v95, v82
	v_mov_b32_e32 v96, v82
	v_mov_b32_e32 v97, v82
	v_mov_b32_e32 v74, v82
	v_mov_b32_e32 v75, v82
	v_mov_b32_e32 v76, v82
	v_mov_b32_e32 v77, v82
	v_mov_b32_e32 v78, v82
	v_mov_b32_e32 v79, v82
	v_mov_b32_e32 v80, v82
	v_mov_b32_e32 v81, v82

; template <int MODE, bool SAMPLE>
; __device__ __forceinline__ void attn_unit(const Params& p, char* lds, int b, int h, int qb) {
;     ...
;         WRITET(buf, stg2[NS == 2 ? par : 0]);
;         if (j >= NS) LOADT(j - NS, stg2[NS == 2 ? par : 0]);
;         __syncthreads();
;         if (wact && j <= jd && var < 2) {
;             const char* Kt = K_lds + buf * 16384; const int vb = vb0 + buf * 16384;
;     ...
;                 p0 = f32x16{}; p1 = f32x16{};
;                 qkt(p0, p1, Kt, Qs, r32, hi);
.LBB0_867:
	s_setprio 0
	s_add_i32 s3, s3, -1
	s_addk_i32 s52, 0xff80
	s_add_u32 s64, s64, 0xfff80000
	s_addc_u32 s65, s65, -1
	s_cmp_eq_u32 s3, -1
	s_cbranch_scc1 .LBB0_876
.LBB0_868:
	v_cndmask_b32_e64 v66, 0, 1, s[72:73]
	s_cmp_lt_u32 s3, 8
	v_cmp_ne_u32_e64 s[0:1], 1, v66
	s_cbranch_scc0 .Lfsr_first_s2
	v_and_b32_e32 v76, 15, v183
	v_bfe_u32 v77, v183, 4, 3
	v_xor_b32_e32 v78, v76, v77
	v_lshrrev_b32_e32 v74, 1, v76
	v_xor_b32_e32 v74, v74, v77
	v_sub_u32_e32 v74, v74, v78
	v_and_b32_e32 v78, 1, v76
	v_lshlrev_b32_e32 v74, 4, v74
	v_lshl_add_u32 v74, v78, 3, v74
	v_lshrrev_b32_e32 v75, 3, v76
	v_lshrrev_b32_e32 v78, 2, v76
	v_sub_u32_e32 v75, v75, v78
	v_lshlrev_b32_e32 v75, 9, v75
	v_and_b32_e32 v78, 7, v76
	v_lshl_add_u32 v75, v78, 3, v75
	v_and_b32_e32 v78, 3, v76
	v_lshlrev_b32_e32 v78, 4, v78
	v_sub_u32_e32 v75, v75, v78
	v_add_u32_e32 v70, v198, v74
	v_add_u32_e32 v71, v199, v74
	v_add_u32_e32 v72, v200, v75
	v_add_u32_e32 v73, v201, v75
	s_waitcnt vmcnt(6)
	v_cvt_pk_bf16_f32 v66, v102, v103
	v_cvt_pk_bf16_f32 v67, v104, v105
	v_cvt_pk_bf16_f32 v68, v98, v99
	v_cvt_pk_bf16_f32 v69, v100, v101
	ds_write_b64 v70, v[66:67] offset:16384
	ds_write_b64 v70, v[68:69] offset:16512
	s_waitcnt vmcnt(4)
	v_cvt_pk_bf16_f32 v66, v110, v111
	v_cvt_pk_bf16_f32 v67, v112, v113
	v_cvt_pk_bf16_f32 v68, v106, v107
	v_cvt_pk_bf16_f32 v69, v108, v109
	ds_write_b64 v71, v[66:67] offset:16384
	ds_write_b64 v71, v[68:69] offset:16512
	s_waitcnt vmcnt(2)
	v_cvt_pk_bf16_f32 v66, v118, v119
	v_cvt_pk_bf16_f32 v67, v120, v121
	v_cvt_pk_bf16_f32 v68, v114, v115
	v_cvt_pk_bf16_f32 v69, v116, v117
	ds_write_b64 v72, v[66:67] offset:49152
	ds_write_b64 v72, v[68:69] offset:50176
	s_waitcnt vmcnt(0)
	v_cvt_pk_bf16_f32 v66, v126, v127
	v_cvt_pk_bf16_f32 v67, v128, v129
	v_cvt_pk_bf16_f32 v68, v122, v123
	v_cvt_pk_bf16_f32 v69, v124, v125
	ds_write_b64 v73, v[66:67] offset:49152
	ds_write_b64 v73, v[68:69] offset:50176
	v_lshl_add_u64 v[66:67], v[166:167], 0, s[64:65]
	v_and_b32_e32 v72, 15, v183
	v_lshlrev_b32_e32 v72, 4, v72
	v_sub_co_u32_e32 v66, vcc, v66, v72
	s_nop 1
	v_subbrev_co_u32_e32 v67, vcc, 0, v67, vcc
	v_add_co_u32_e32 v70, vcc, s83, v66
	v_lshl_add_u64 v[68:69], v[66:67], 0, s[56:57]
	s_nop 0
	v_addc_co_u32_e32 v71, vcc, 0, v67, vcc
	s_mov_b32 s6, 0x420000
	global_load_dwordx4 v[102:105], v[70:71], off nt
	global_load_dwordx4 v[98:101], v[68:69], off offset:256 nt
	v_lshl_add_u64 v[68:69], v[66:67], 0, s[58:59]
	v_add_co_u32_e32 v66, vcc, s6, v66
	s_nop 1
	v_addc_co_u32_e32 v67, vcc, 0, v67, vcc
	global_load_dwordx4 v[110:113], v[66:67], off nt
	global_load_dwordx4 v[106:109], v[68:69], off offset:256 nt
	v_lshl_add_u64 v[66:67], v[168:169], 0, s[64:65]
	v_and_b32_e32 v72, 15, v183
	v_lshlrev_b32_e32 v72, 4, v72
	v_sub_co_u32_e32 v66, vcc, v66, v72
	s_nop 1
	v_subbrev_co_u32_e32 v67, vcc, 0, v67, vcc
	v_add_co_u32_e32 v70, vcc, s83, v66
	v_lshl_add_u64 v[68:69], v[66:67], 0, s[56:57]
	s_nop 0
	v_addc_co_u32_e32 v71, vcc, 0, v67, vcc
	global_load_dwordx4 v[118:121], v[70:71], off nt
	global_load_dwordx4 v[114:117], v[68:69], off offset:256 nt
	v_lshl_add_u64 v[68:69], v[66:67], 0, s[58:59]
	v_add_co_u32_e32 v66, vcc, 0x420000, v66
	s_nop 1
	v_addc_co_u32_e32 v67, vcc, 0, v67, vcc
	global_load_dwordx4 v[126:129], v[66:67], off nt
	global_load_dwordx4 v[122:125], v[68:69], off offset:256 nt
	s_and_b64 vcc, exec, s[0:1]
	s_waitcnt lgkmcnt(0)
	s_barrier
	s_cbranch_vccnz .LBB0_871
	s_setprio 2
	ds_read_b128 v[66:69], v203 offset:16384
	v_add_u32_e32 v70, s2, v181
	ds_read_b128 v[70:73], v70
	ds_read_b128 v[74:77], v203 offset:24576
	v_add_u32_e32 v78, s2, v182
	ds_read_b128 v[212:215], v78
	ds_read_b128 v[216:219], v204 offset:16384
	ds_read_b128 v[220:223], v204 offset:24576
	v_add_u32_e32 v149, s2, v184
	s_waitcnt lgkmcnt(4)
	v_mfma_f32_32x32x16_bf16 v[82:97], v[66:69], v[70:73], 0
	s_waitcnt lgkmcnt(3)
	v_mfma_f32_32x32x16_bf16 v[66:81], v[74:77], v[70:73], 0
	s_waitcnt lgkmcnt(1)
	v_mfma_f32_32x32x16_bf16 v[82:97], v[216:219], v[212:215], v[82:97]
	s_waitcnt lgkmcnt(0)
	v_mfma_f32_32x32x16_bf16 v[66:81], v[220:223], v[212:215], v[66:81]
	ds_read_b128 v[212:215], v205 offset:16384
	ds_read_b128 v[216:219], v149
	ds_read_b128 v[220:223], v205 offset:24576
	v_add_u32_e32 v149, s2, v185
	ds_read_b128 v[224:227], v149
	v_add_u32_e32 v149, s2, v186
	s_waitcnt lgkmcnt(2)
	v_mfma_f32_32x32x16_bf16 v[82:97], v[212:215], v[216:219], v[82:97]
	s_waitcnt lgkmcnt(1)
	v_mfma_f32_32x32x16_bf16 v[66:81], v[220:223], v[216:219], v[66:81]
	ds_read_b128 v[212:215], v206 offset:16384
	ds_read_b128 v[216:219], v206 offset:24576
	s_waitcnt lgkmcnt(1)
	v_mfma_f32_32x32x16_bf16 v[82:97], v[212:215], v[224:227], v[82:97]
	ds_read_b128 v[212:215], v207 offset:16384
	s_waitcnt lgkmcnt(1)
	v_mfma_f32_32x32x16_bf16 v[66:81], v[216:219], v[224:227], v[66:81]
	ds_read_b128 v[216:219], v149
	ds_read_b128 v[220:223], v207 offset:24576
	v_add_u32_e32 v149, s2, v187
	ds_read_b128 v[224:227], v149
	v_add_u32_e32 v149, s2, v188
	s_waitcnt lgkmcnt(1)
	v_mfma_f32_32x32x16_bf16 v[66:81], v[220:223], v[216:219], v[66:81]
	v_mfma_f32_32x32x16_bf16 v[82:97], v[212:215], v[216:219], v[82:97]
	ds_read_b128 v[212:215], v208 offset:16384
	ds_read_b128 v[216:219], v208 offset:24576
	s_waitcnt lgkmcnt(0)
	v_mfma_f32_32x32x16_bf16 v[66:81], v[216:219], v[224:227], v[66:81]
	v_mfma_f32_32x32x16_bf16 v[82:97], v[212:215], v[224:227], v[82:97]
	ds_read_b128 v[212:215], v209 offset:16384
	ds_read_b128 v[216:219], v149
	ds_read_b128 v[220:223], v209 offset:24576
	v_add_u32_e32 v149, s2, v189
	ds_read_b128 v[224:227], v149
	s_waitcnt lgkmcnt(1)
; __device__ __forceinline__ int crow(int r, int hi) { return (r & 3) + 8 * (r >> 2) + 4 * hi; }
; __device__ __forceinline__ void qkt(f32x16& p0, f32x16& p1, const char* Ks, const char* Qs, int r32, int hi) {
; #pragma unroll
;     for (int d0 = 0; d0 < 8; ++d0) { const int cb = (d0 * 16 + hi * 8) * 2;
;         const bf16x8 qv = *reinterpret_cast<const bf16x8*>(Qs + KSWZ(r32, cb));
;         const bf16x8 b0 = *reinterpret_cast<const bf16x8*>(Ks + KSWZ(r32, cb));
;         const bf16x8 b1 = *reinterpret_cast<const bf16x8*>(Ks + KSWZ(32 + r32, cb));
;         p0 = __builtin_amdgcn_mfma_f32_32x32x16_bf16(b0, qv, p0, 0, 0, 0);
;         p1 = __builtin_amdgcn_mfma_f32_32x32x16_bf16(b1, qv, p1, 0, 0, 0); }
; template <int MODE, bool SAMPLE>
; __device__ __forceinline__ void attn_unit(const Params& p, char* lds, int b, int h, int qb) {
;     ...
;                 p0 = f32x16{}; p1 = f32x16{};
;                 qkt(p0, p1, Kt, Qs, r32, hi);
;                 if (j == jd) {
; #pragma unroll
;                     for (int r = 0; r < 16; ++r) { const int kp = j * 64 + crow(r, hi); if (kp >= qpos) p0[r] = -1e30f; if (kp + 32 >= qpos) p1[r] = -1e30f; } }
;                 f32x16 s0, s1;
; #pragma unroll
;                 for (int r = 0; r < 16; ++r) { p0[r] = __builtin_amdgcn_exp2f(fminf(p0[r], 100.f)); p1[r] = __builtin_amdgcn_exp2f(fminf(p1[r], 100.f));
;                     s0[r] = __builtin_amdgcn_rcpf(1.f + p0[r]); s1[r] = __builtin_amdgcn_rcpf(1.f + p1[r]); }
;                 float run = carry, bs[8];
; #pragma unroll
;                 for (int i = 7; i >= 0; --i) { const f32x16& S = (i >= 4) ? s1 : s0; const int rb = 4 * (i & 3);
;                     const float gs = (S[rb] * S[rb + 1]) * (S[rb + 2] * S[rb + 3]);
;                     auto rr = __builtin_amdgcn_permlane32_swap(__float_as_uint(gs), __float_as_uint(gs), false, false);
;                     const float glo = __uint_as_float(rr[0]), ghi = __uint_as_float(rr[1]);
;                     const float exH = run; run *= ghi; const float exL = run; run *= glo;
;                     bs[i] = hi ? exH : exL; }
;                 carry = run;
	v_mfma_f32_32x32x16_bf16 v[66:81], v[220:223], v[216:219], v[66:81]
	v_mfma_f32_32x32x16_bf16 v[82:97], v[212:215], v[216:219], v[82:97]
	ds_read_b128 v[212:215], v210 offset:16384
	ds_read_b128 v[216:219], v210 offset:24576
	s_waitcnt lgkmcnt(0)
	v_mfma_f32_32x32x16_bf16 v[66:81], v[216:219], v[224:227], v[66:81]
	v_mfma_f32_32x32x16_bf16 v[82:97], v[212:215], v[224:227], v[82:97]
	s_nop 10
	v_max_f32_e32 v69, v69, v69
	v_min_f32_e32 v69, 0x42c80000, v69
	v_exp_f32_e32 v215, v69
	v_max_f32_e32 v81, v81, v81
	v_min_f32_e32 v81, 0x42c80000, v81
	v_max_f32_e32 v68, v68, v68
	v_max_f32_e32 v66, v66, v66
	v_max_f32_e32 v69, v86, v86
	v_min_f32_e32 v69, 0x42c80000, v69
	v_exp_f32_e32 v86, v69
	v_max_f32_e32 v69, v70, v70
	v_max_f32_e32 v70, v87, v87
	v_min_f32_e32 v70, 0x42c80000, v70
	v_exp_f32_e32 v87, v70
	v_max_f32_e32 v70, v71, v71
	v_max_f32_e32 v71, v88, v88
	v_min_f32_e32 v71, 0x42c80000, v71
	v_exp_f32_e32 v88, v71
	v_max_f32_e32 v71, v72, v72
	v_max_f32_e32 v72, v89, v89
	v_min_f32_e32 v72, 0x42c80000, v72
	v_exp_f32_e32 v89, v72
	v_max_f32_e32 v72, v73, v73
	v_max_f32_e32 v73, v90, v90
	v_min_f32_e32 v73, 0x42c80000, v73
	v_exp_f32_e32 v90, v73
	v_max_f32_e32 v73, v74, v74
	v_max_f32_e32 v74, v91, v91
	v_min_f32_e32 v74, 0x42c80000, v74
	v_exp_f32_e32 v91, v74
	v_max_f32_e32 v74, v75, v75
	v_max_f32_e32 v75, v92, v92
	v_min_f32_e32 v75, 0x42c80000, v75
	v_exp_f32_e32 v92, v75
	v_max_f32_e32 v75, v76, v76
	v_max_f32_e32 v76, v93, v93
	v_min_f32_e32 v76, 0x42c80000, v76
	v_exp_f32_e32 v93, v76
	v_max_f32_e32 v76, v77, v77
	v_max_f32_e32 v77, v94, v94
	v_min_f32_e32 v77, 0x42c80000, v77
	v_exp_f32_e32 v94, v77
	v_max_f32_e32 v77, v78, v78
	v_max_f32_e32 v78, v95, v95
	v_min_f32_e32 v78, 0x42c80000, v78
	v_exp_f32_e32 v95, v78
	v_max_f32_e32 v78, v79, v79
	v_max_f32_e32 v79, v96, v96
	v_min_f32_e32 v79, 0x42c80000, v79
	v_min_f32_e32 v77, 0x42c80000, v77
	v_exp_f32_e32 v96, v79
	v_max_f32_e32 v79, v80, v80
	v_exp_f32_e32 v233, v77
	v_min_f32_e32 v79, 0x42c80000, v79
	v_min_f32_e32 v78, 0x42c80000, v78
	v_exp_f32_e32 v237, v79
	v_exp_f32_e32 v235, v78
	v_max_f32_e32 v80, v97, v97
	v_exp_f32_e32 v97, v81
	v_min_f32_e32 v73, 0x42c80000, v73
	v_add_f32_e32 v77, 1.0, v233
	v_exp_f32_e32 v225, v73
	v_rcp_f32_e32 v236, v77
	v_add_f32_e32 v77, 1.0, v95
	v_add_f32_e32 v79, 1.0, v237
	v_min_f32_e32 v74, 0x42c80000, v74
	v_min_f32_e32 v75, 0x42c80000, v75
	v_min_f32_e32 v76, 0x42c80000, v76
	v_rcp_f32_e32 v78, v77
	v_add_f32_e32 v77, 1.0, v235
	v_rcp_f32_e32 v240, v79
	v_add_f32_e32 v79, 1.0, v97
	v_exp_f32_e32 v227, v74
	v_exp_f32_e32 v229, v75
	v_exp_f32_e32 v231, v76
	v_rcp_f32_e32 v238, v77
	v_rcp_f32_e32 v241, v79
	v_min_f32_e32 v69, 0x42c80000, v69
	v_add_f32_e32 v73, 1.0, v225
	v_max_f32_e32 v83, v83, v83
	v_exp_f32_e32 v217, v69
	v_rcp_f32_e32 v228, v73
	v_add_f32_e32 v73, 1.0, v91
	v_min_f32_e32 v80, 0x42c80000, v80
	v_min_f32_e32 v83, 0x42c80000, v83
	v_min_f32_e32 v70, 0x42c80000, v70
	v_min_f32_e32 v71, 0x42c80000, v71
	v_min_f32_e32 v72, 0x42c80000, v72
	v_rcp_f32_e32 v74, v73
	v_add_f32_e32 v73, 1.0, v227
	v_add_f32_e32 v75, 1.0, v229
	v_add_f32_e32 v76, 1.0, v231
	v_exp_f32_e32 v239, v80
	v_mul_f32_e32 v80, v236, v238
	v_mul_f32_e32 v81, v240, v241
	v_exp_f32_e32 v163, v83
	v_max_f32_e32 v83, v84, v84
	v_exp_f32_e32 v219, v70
	v_exp_f32_e32 v221, v71
	v_exp_f32_e32 v223, v72
	v_rcp_f32_e32 v230, v73
	v_rcp_f32_e32 v232, v75
	v_rcp_f32_e32 v234, v76
	v_mul_f32_e32 v80, v80, v81
	v_min_f32_e32 v83, 0x42c80000, v83
	v_mov_b32_e32 v81, v80
	v_exp_f32_e32 v84, v83
	v_min_f32_e32 v68, 0x42c80000, v68
	v_max_f32_e32 v83, v85, v85
	v_add_f32_e32 v69, 1.0, v217
	v_permlane32_swap_b32_e32 v80, v81
	v_min_f32_e32 v66, 0x42c80000, v66
	v_max_f32_e32 v67, v67, v67
	v_exp_f32_e32 v213, v68
	v_min_f32_e32 v83, 0x42c80000, v83
	v_rcp_f32_e32 v220, v69
	v_add_f32_e32 v69, 1.0, v87
	v_mul_f32_e32 v81, v147, v81
	v_exp_f32_e32 v161, v66
	v_min_f32_e32 v67, 0x42c80000, v67
	v_exp_f32_e32 v85, v83
	v_rcp_f32_e32 v70, v69
	v_add_f32_e32 v69, 1.0, v219
	v_add_f32_e32 v71, 1.0, v221
	v_add_f32_e32 v72, 1.0, v223
	v_mul_f32_e32 v80, v81, v80
	v_cndmask_b32_e64 v147, v147, v81, s[12:13]
	v_mul_f32_e32 v81, v228, v230
	v_mul_f32_e32 v242, v232, v234
	v_exp_f32_e32 v211, v67
	v_rcp_f32_e32 v222, v69
	v_rcp_f32_e32 v224, v71
	v_rcp_f32_e32 v226, v72
	v_mul_f32_e32 v81, v81, v242
	v_max_f32_e32 v82, v82, v82
	v_mov_b32_e32 v242, v81
	v_min_f32_e32 v82, 0x42c80000, v82
	v_add_f32_e32 v68, 1.0, v213
	v_permlane32_swap_b32_e32 v81, v242
	v_exp_f32_e32 v149, v82
	v_add_f32_e32 v82, 1.0, v161
	v_add_f32_e32 v67, 1.0, v163
	v_rcp_f32_e32 v216, v68
	v_add_f32_e32 v68, 1.0, v85
	v_mul_f32_e32 v242, v80, v242
	v_rcp_f32_e32 v212, v82
	v_rcp_f32_e32 v82, v67
	v_add_f32_e32 v67, 1.0, v211
	v_rcp_f32_e32 v83, v68
	v_add_f32_e32 v68, 1.0, v215
	v_mul_f32_e32 v81, v242, v81
	v_cndmask_b32_e64 v242, v80, v242, s[12:13]
	v_mul_f32_e32 v80, v220, v222
	v_mul_f32_e32 v243, v224, v226
	v_rcp_f32_e32 v214, v67
	v_rcp_f32_e32 v218, v68
	v_mul_f32_e32 v80, v80, v243
	v_mov_b32_e32 v243, v80
	s_nop 1
	v_permlane32_swap_b32_e32 v80, v243
	v_mul_f32_e32 v243, v81, v243
	v_add_f32_e32 v76, 1.0, v94
	v_add_f32_e32 v77, 1.0, v96
	v_add_f32_e32 v79, 1.0, v239
	v_mul_f32_e32 v80, v243, v80
	v_cndmask_b32_e64 v243, v81, v243, s[12:13]
	v_mul_f32_e32 v81, v212, v214
	v_mul_f32_e32 v244, v216, v218
	v_rcp_f32_e32 v76, v76
	v_rcp_f32_e32 v77, v77
	v_rcp_f32_e32 v79, v79
	v_mul_f32_e32 v81, v81, v244
	v_mov_b32_e32 v244, v81
	s_nop 1
	v_permlane32_swap_b32_e32 v81, v244
	v_mul_f32_e32 v244, v80, v244
	v_add_f32_e32 v72, 1.0, v90
	v_add_f32_e32 v73, 1.0, v92
	v_add_f32_e32 v75, 1.0, v93
; #define SBAR() __builtin_amdgcn_sched_barrier(0)
; template <int OFF> __device__ __forceinline__ s16x4 tr_read(int vb) { s16x4 r; asm volatile("ds_read_b64_tr_b16 %0, %1 offset:%2" : "=&v"(r) : "v"(vb), "i"(OFF) : "memory"); return r; }
; template <int D0> __device__ __forceinline__ void pv_one(f32x16& od, int vb, bf16x8 pa0, bf16x8 pa1, bf16x8 pa2, bf16x8 pa3) {
;     const s16x4 l0 = tr_read<v_rd_off(D0, 0, 0)>(vb), h0 = tr_read<v_rd_off(D0, 0, 1)>(vb), l1 = tr_read<v_rd_off(D0, 1, 0)>(vb), h1 = tr_read<v_rd_off(D0, 1, 1)>(vb);
;     const s16x4 l2 = tr_read<v_rd_off(D0, 2, 0)>(vb), h2 = tr_read<v_rd_off(D0, 2, 1)>(vb), l3 = tr_read<v_rd_off(D0, 3, 0)>(vb), h3 = tr_read<v_rd_off(D0, 3, 1)>(vb);
;     asm volatile("s_waitcnt lgkmcnt(0)" ::: "memory"); SBAR();
;     ...
;     od = __builtin_amdgcn_mfma_f32_32x32x16_bf16(pa0, PKV(l0, h0), od, 0, 0, 0);
;     od = __builtin_amdgcn_mfma_f32_32x32x16_bf16(pa1, PKV(l1, h1), od, 0, 0, 0);
;     od = __builtin_amdgcn_mfma_f32_32x32x16_bf16(pa2, PKV(l2, h2), od, 0, 0, 0);
;     od = __builtin_amdgcn_mfma_f32_32x32x16_bf16(pa3, PKV(l3, h3), od, 0, 0, 0);
;     ...
; }
; __device__ __forceinline__ void pv_d0(f32x16* o, int vb, bf16x8 pa0, bf16x8 pa1, bf16x8 pa2, bf16x8 pa3) {
;     pv_one<0>(o[0], vb, pa0, pa1, pa2, pa3); pv_one<1>(o[1], vb, pa0, pa1, pa2, pa3); pv_one<2>(o[2], vb, pa0, pa1, pa2, pa3); pv_one<3>(o[3], vb, pa0, pa1, pa2, pa3);
; }
; template <int MODE, bool SAMPLE>
; __device__ __forceinline__ void attn_unit(const Params& p, char* lds, int b, int h, int qb) {
;     ...
;                 carry = run;
; #pragma unroll
;                 for (int i = 0; i < 8; ++i) { f32x16& S = (i >= 4) ? s1 : s0; f32x16& Z = (i >= 4) ? p1 : p0; const int rb = 4 * (i & 3);
;                     const float i3 = bs[i] * S[rb + 3], i2 = i3 * S[rb + 2], i1 = i2 * S[rb + 1], i0 = i1 * S[rb];
;                     Z[rb + 3] *= i3; Z[rb + 2] *= i2; Z[rb + 1] *= i1; Z[rb] *= i0; }
;             }
;             PK4(p0, 0, pa0); PK4(p0, 8, pa1); PK4(p1, 0, pa2); PK4(p1, 8, pa3);
;             pv_d0(o, vb, pa0, pa1, pa2, pa3);
	v_mul_f32_e32 v245, v244, v81
	v_cndmask_b32_e64 v244, v80, v244, s[12:13]
	v_pk_mul_f32 v[80:81], v[76:77], v[78:79]
	v_rcp_f32_e32 v72, v72
	v_rcp_f32_e32 v73, v73
	v_rcp_f32_e32 v75, v75
	v_pk_mul_f32 v[80:81], v[80:81], v[80:81] op_sel:[0,1] op_sel_hi:[1,0]
	v_add_f32_e32 v68, 1.0, v86
	v_mov_b32_e32 v81, v80
	s_nop 1
	v_permlane32_swap_b32_e32 v80, v81
	v_mul_f32_e32 v81, v245, v81
	v_add_f32_e32 v69, 1.0, v88
	v_add_f32_e32 v71, 1.0, v89
	v_mul_f32_e32 v246, v81, v80
	v_cndmask_b32_e64 v245, v245, v81, s[12:13]
	v_pk_mul_f32 v[80:81], v[72:73], v[74:75]
	v_rcp_f32_e32 v68, v68
	v_rcp_f32_e32 v69, v69
	v_rcp_f32_e32 v71, v71
	v_pk_mul_f32 v[80:81], v[80:81], v[80:81] op_sel:[0,1] op_sel_hi:[1,0]
	v_add_f32_e32 v66, 1.0, v149
	v_mov_b32_e32 v81, v80
	s_nop 1
	v_permlane32_swap_b32_e32 v80, v81
	v_mul_f32_e32 v81, v246, v81
	v_add_f32_e32 v67, 1.0, v84
	v_mul_f32_e32 v247, v81, v80
	v_cndmask_b32_e64 v246, v246, v81, s[12:13]
	v_pk_mul_f32 v[80:81], v[68:69], v[70:71]
	v_rcp_f32_e32 v66, v66
	v_rcp_f32_e32 v67, v67
	v_pk_mul_f32 v[80:81], v[80:81], v[80:81] op_sel:[0,1] op_sel_hi:[1,0]
	v_mul_f32_e32 v75, v75, v246
	v_mov_b32_e32 v81, v80
	s_nop 1
	v_permlane32_swap_b32_e32 v80, v81
	v_mul_f32_e32 v81, v247, v81
	v_mul_f32_e32 v248, v81, v80
	v_cndmask_b32_e64 v247, v247, v81, s[12:13]
	v_pk_mul_f32 v[80:81], v[66:67], v[82:83]
	v_mul_f32_e32 v71, v71, v247
	v_pk_mul_f32 v[80:81], v[80:81], v[80:81] op_sel:[0,1] op_sel_hi:[1,0]
	v_mul_f32_e32 v69, v69, v71
	v_mov_b32_e32 v81, v80
	s_nop 1
	v_permlane32_swap_b32_e32 v80, v81
	v_mul_f32_e32 v81, v248, v81
	v_cndmask_b32_e64 v248, v248, v81, s[12:13]
	v_mul_f32_e32 v83, v83, v248
	v_mul_f32_e32 v67, v67, v83
	v_mul_f32_e32 v79, v79, v245
	v_mul_f32_e32 v82, v82, v67
	v_mul_f32_e32 v67, v84, v67
	v_mul_f32_e32 v70, v70, v69
	v_mul_f32_e32 v73, v73, v75
	v_mul_f32_e32 v77, v77, v79
	v_mul_f32_e32 v84, v218, v244
	v_mul_f32_e32 v83, v85, v83
	v_mul_f32_e32 v68, v68, v70
	v_mul_f32_e32 v69, v88, v69
	v_mul_f32_e32 v74, v74, v73
	v_mul_f32_e32 v73, v92, v73
	v_mul_f32_e32 v78, v78, v77
	v_mul_f32_e32 v77, v96, v77
	v_mul_f32_e32 v85, v216, v84
	v_mul_f32_e32 v88, v226, v243
	v_mul_f32_e32 v92, v234, v242
	v_mul_f32_e32 v96, v241, v147
	v_mul_f32_e32 v66, v66, v82
	v_mul_f32_e32 v71, v89, v71
	v_mul_f32_e32 v68, v86, v68
	v_mul_f32_e32 v72, v72, v74
	v_mul_f32_e32 v75, v93, v75
	v_mul_f32_e32 v76, v76, v78
	v_mul_f32_e32 v86, v214, v85
	v_mul_f32_e32 v89, v224, v88
	v_mul_f32_e32 v93, v232, v92
	v_mul_f32_e32 v147, v240, v96
	v_mul_f32_e32 v66, v149, v66
	v_mul_f32_e32 v70, v87, v70
	v_mul_f32_e32 v72, v90, v72
	v_mul_f32_e32 v76, v94, v76
	v_mul_f32_e32 v87, v212, v86
	v_mul_f32_e32 v90, v222, v89
	v_mul_f32_e32 v94, v230, v93
	v_mul_f32_e32 v149, v238, v147
	v_mul_f32_e32 v82, v163, v82
	v_mul_f32_e32 v74, v91, v74
	v_mul_f32_e32 v79, v239, v79
	v_mul_f32_e32 v78, v95, v78
	v_mul_f32_e32 v87, v161, v87
	v_mul_f32_e32 v91, v220, v90
	v_mul_f32_e32 v95, v228, v94
	v_mul_f32_e32 v161, v236, v149
	v_mul_f32_e32 v84, v215, v84
	v_mul_f32_e32 v85, v213, v85
	v_mul_f32_e32 v86, v211, v86
	v_mul_f32_e32 v88, v223, v88
	v_mul_f32_e32 v89, v221, v89
	v_mul_f32_e32 v90, v219, v90
	v_mul_f32_e32 v91, v217, v91
	v_mul_f32_e32 v92, v231, v92
	v_mul_f32_e32 v93, v229, v93
	v_mul_f32_e32 v94, v227, v94
	v_mul_f32_e32 v95, v225, v95
	v_mul_f32_e32 v96, v97, v96
	v_mul_f32_e32 v97, v237, v147
	v_mul_f32_e32 v149, v235, v149
	v_mul_f32_e32 v161, v233, v161
	v_mul_f32_e32 v147, v81, v80
	v_cvt_pk_bf16_f32 v66, v66, v82
	v_cvt_pk_bf16_f32 v67, v67, v83
	v_cvt_pk_bf16_f32 v68, v68, v70
	v_cvt_pk_bf16_f32 v69, v69, v71
	v_cvt_pk_bf16_f32 v70, v72, v74
	v_cvt_pk_bf16_f32 v71, v73, v75
	v_cvt_pk_bf16_f32 v72, v76, v78
	v_cvt_pk_bf16_f32 v73, v77, v79
	v_cvt_pk_bf16_f32 v74, v87, v86
	v_cvt_pk_bf16_f32 v75, v85, v84
	v_cvt_pk_bf16_f32 v76, v91, v90
	v_cvt_pk_bf16_f32 v77, v89, v88
	v_cvt_pk_bf16_f32 v78, v95, v94
	v_cvt_pk_bf16_f32 v79, v93, v92
	v_cvt_pk_bf16_f32 v80, v161, v149
	v_cvt_pk_bf16_f32 v81, v97, v96
	ds_read_b64_tr_b16 v[82:83], v190 offset:0
	ds_read_b64_tr_b16 v[84:85], v190 offset:0x800
	ds_read_b64_tr_b16 v[86:87], v190 offset:0x1000
	ds_read_b64_tr_b16 v[88:89], v190 offset:0x1800
	ds_read_b64_tr_b16 v[90:91], v190 offset:0x2000
	ds_read_b64_tr_b16 v[92:93], v190 offset:0x2800
	ds_read_b64_tr_b16 v[94:95], v190 offset:0x3000
	ds_read_b64_tr_b16 v[96:97], v190 offset:0x3800
	s_waitcnt lgkmcnt(0)
	s_nop 0
	v_permlane32_swap_b32_e32 v66, v68
	v_permlane32_swap_b32_e32 v67, v69
	v_permlane32_swap_b32_e32 v70, v72
	v_permlane32_swap_b32_e32 v71, v73
	v_permlane32_swap_b32_e32 v74, v76
	v_permlane32_swap_b32_e32 v75, v77
	v_permlane32_swap_b32_e32 v78, v80
	v_permlane32_swap_b32_e32 v79, v81
	v_mfma_f32_32x32x16_bf16 v[2:17], v[66:69], v[82:85], v[2:17]
	ds_read_b64_tr_b16 v[82:83], v190 offset:0x200
	ds_read_b64_tr_b16 v[84:85], v190 offset:0xa00
	v_mfma_f32_32x32x16_bf16 v[2:17], v[70:73], v[86:89], v[2:17]
	ds_read_b64_tr_b16 v[86:87], v190 offset:0x1200
	ds_read_b64_tr_b16 v[88:89], v190 offset:0x1a00
	v_mfma_f32_32x32x16_bf16 v[2:17], v[74:77], v[90:93], v[2:17]
	ds_read_b64_tr_b16 v[90:91], v190 offset:0x2200
	ds_read_b64_tr_b16 v[92:93], v190 offset:0x2a00
	v_mfma_f32_32x32x16_bf16 v[2:17], v[78:81], v[94:97], v[2:17]
	ds_read_b64_tr_b16 v[94:95], v190 offset:0x3200
	ds_read_b64_tr_b16 v[96:97], v190 offset:0x3a00
	s_waitcnt lgkmcnt(0)
	v_mfma_f32_32x32x16_bf16 v[50:65], v[66:69], v[82:85], v[50:65]
	ds_read_b64_tr_b16 v[82:83], v190 offset:0x400
	ds_read_b64_tr_b16 v[84:85], v190 offset:0xc00
	v_mfma_f32_32x32x16_bf16 v[50:65], v[70:73], v[86:89], v[50:65]
	ds_read_b64_tr_b16 v[86:87], v190 offset:0x1400
	ds_read_b64_tr_b16 v[88:89], v190 offset:0x1c00
	v_mfma_f32_32x32x16_bf16 v[50:65], v[74:77], v[90:93], v[50:65]
	ds_read_b64_tr_b16 v[90:91], v190 offset:0x2400
	ds_read_b64_tr_b16 v[92:93], v190 offset:0x2c00
	v_mfma_f32_32x32x16_bf16 v[50:65], v[78:81], v[94:97], v[50:65]
	ds_read_b64_tr_b16 v[94:95], v190 offset:0x3400
	ds_read_b64_tr_b16 v[96:97], v190 offset:0x3c00
	s_waitcnt lgkmcnt(0)
	v_mfma_f32_32x32x16_bf16 v[34:49], v[66:69], v[82:85], v[34:49]
	ds_read_b64_tr_b16 v[82:83], v190 offset:0x600
	ds_read_b64_tr_b16 v[84:85], v190 offset:0xe00
	v_mfma_f32_32x32x16_bf16 v[34:49], v[70:73], v[86:89], v[34:49]
	ds_read_b64_tr_b16 v[86:87], v190 offset:0x1600
	ds_read_b64_tr_b16 v[88:89], v190 offset:0x1e00
	v_mfma_f32_32x32x16_bf16 v[34:49], v[74:77], v[90:93], v[34:49]
	ds_read_b64_tr_b16 v[90:91], v190 offset:0x2600
	ds_read_b64_tr_b16 v[92:93], v190 offset:0x2e00
	v_mfma_f32_32x32x16_bf16 v[34:49], v[78:81], v[94:97], v[34:49]
	ds_read_b64_tr_b16 v[94:95], v190 offset:0x3600
	ds_read_b64_tr_b16 v[96:97], v190 offset:0x3e00
	s_waitcnt lgkmcnt(0)
	v_mfma_f32_32x32x16_bf16 v[18:33], v[66:69], v[82:85], v[18:33]
	v_mfma_f32_32x32x16_bf16 v[18:33], v[70:73], v[86:89], v[18:33]
	v_mfma_f32_32x32x16_bf16 v[18:33], v[74:77], v[90:93], v[18:33]
	v_mfma_f32_32x32x16_bf16 v[18:33], v[78:81], v[94:97], v[18:33]
; template <int MODE, bool SAMPLE>
; __device__ __forceinline__ void attn_unit(const Params& p, char* lds, int b, int h, int qb) {
;     ...
;         WRITET(buf, stg2[NS == 2 ? par : 0]);
.LBB0_871:
	s_setprio 0
	v_and_b32_e32 v76, 15, v183
	v_bfe_u32 v77, v183, 4, 3
	v_xor_b32_e32 v78, v76, v77
	v_lshrrev_b32_e32 v74, 1, v76
	v_xor_b32_e32 v74, v74, v77
	v_sub_u32_e32 v74, v74, v78
	v_and_b32_e32 v78, 1, v76
	v_lshlrev_b32_e32 v74, 4, v74
	v_lshl_add_u32 v74, v78, 3, v74
	v_lshrrev_b32_e32 v75, 3, v76
	v_lshrrev_b32_e32 v78, 2, v76
	v_sub_u32_e32 v75, v75, v78
	v_lshlrev_b32_e32 v75, 9, v75
	v_and_b32_e32 v78, 7, v76
	v_lshl_add_u32 v75, v78, 3, v75
	v_and_b32_e32 v78, 3, v76
	v_lshlrev_b32_e32 v78, 4, v78
	v_sub_u32_e32 v75, v75, v78
	v_add_u32_e32 v70, v198, v74
	v_add_u32_e32 v71, v199, v74
	v_add_u32_e32 v72, v200, v75
	v_add_u32_e32 v73, v201, v75
	s_waitcnt vmcnt(6)
	v_cvt_pk_bf16_f32 v66, v102, v103
	v_cvt_pk_bf16_f32 v67, v104, v105
	s_waitcnt vmcnt(6)
	v_cvt_pk_bf16_f32 v68, v98, v99
	v_cvt_pk_bf16_f32 v69, v100, v101
	ds_write_b64 v70, v[66:67]
	ds_write_b64 v70, v[68:69] offset:128
	s_waitcnt vmcnt(4)
	v_cvt_pk_bf16_f32 v66, v110, v111
	v_cvt_pk_bf16_f32 v67, v112, v113
	s_waitcnt vmcnt(4)
	v_cvt_pk_bf16_f32 v68, v106, v107
	v_cvt_pk_bf16_f32 v69, v108, v109
	ds_write_b64 v71, v[66:67]
	ds_write_b64 v71, v[68:69] offset:128
	s_waitcnt vmcnt(2)
	v_cvt_pk_bf16_f32 v66, v118, v119
	v_cvt_pk_bf16_f32 v67, v120, v121
	s_waitcnt vmcnt(2)
	v_cvt_pk_bf16_f32 v68, v114, v115
	v_cvt_pk_bf16_f32 v69, v116, v117
	s_cmp_eq_u32 s64, 0xffc00000
	ds_write_b64 v72, v[66:67] offset:32768
	ds_write_b64 v72, v[68:69] offset:33792
	s_waitcnt vmcnt(0)
	v_cvt_pk_bf16_f32 v66, v126, v127
	v_cvt_pk_bf16_f32 v67, v128, v129
	s_waitcnt vmcnt(0)
	v_cvt_pk_bf16_f32 v68, v122, v123
	v_cvt_pk_bf16_f32 v69, v124, v125
	ds_write_b64 v73, v[66:67] offset:32768
	ds_write_b64 v73, v[68:69] offset:33792

; __device__ __forceinline__ int crow(int r, int hi) { return (r & 3) + 8 * (r >> 2) + 4 * hi; }
; __device__ __forceinline__ void qkt(f32x16& p0, f32x16& p1, const char* Ks, const char* Qs, int r32, int hi) {
; #pragma unroll
;     for (int d0 = 0; d0 < 8; ++d0) { const int cb = (d0 * 16 + hi * 8) * 2;
;         const bf16x8 qv = *reinterpret_cast<const bf16x8*>(Qs + KSWZ(r32, cb));
;         const bf16x8 b0 = *reinterpret_cast<const bf16x8*>(Ks + KSWZ(r32, cb));
;         const bf16x8 b1 = *reinterpret_cast<const bf16x8*>(Ks + KSWZ(32 + r32, cb));
;         p0 = __builtin_amdgcn_mfma_f32_32x32x16_bf16(b0, qv, p0, 0, 0, 0);
;         p1 = __builtin_amdgcn_mfma_f32_32x32x16_bf16(b1, qv, p1, 0, 0, 0); }
; }
; template <int MODE, bool SAMPLE>
; __device__ __forceinline__ void attn_unit(const Params& p, char* lds, int b, int h, int qb) {
;     ...
;         __syncthreads();
;         if (wact && j <= jd && var < 2) {
;             const char* Kt = K_lds + buf * 16384; const int vb = vb0 + buf * 16384;
;     ...
;                 p0 = f32x16{}; p1 = f32x16{};
;                 qkt(p0, p1, Kt, Qs, r32, hi);
;                 if (j == jd) {
; #pragma unroll
;                     for (int r = 0; r < 16; ++r) { const int kp = j * 64 + crow(r, hi); if (kp >= qpos) p0[r] = -1e30f; if (kp + 32 >= qpos) p1[r] = -1e30f; } }
.LBB0_873:
	s_and_b64 vcc, exec, s[0:1]
	s_waitcnt lgkmcnt(0)
	s_barrier
	s_cbranch_vccnz .LBB0_867
	s_setprio 2
	ds_read_b128 v[66:69], v203
	ds_read_b128 v[86:89], v203 offset:8192
	v_add_u32_e32 v70, s2, v181
	ds_read_b128 v[82:85], v70
	ds_read_b128 v[212:215], v204
	v_add_u32_e32 v149, s2, v182
	ds_read_b128 v[216:219], v149
	v_add_u32_e32 v149, s2, v184
	s_cmp_lg_u32 s64, 0
	s_waitcnt lgkmcnt(2)
	v_mfma_f32_32x32x16_bf16 v[66:81], v[66:69], v[82:85], 0
	s_waitcnt lgkmcnt(0)
	v_mfma_f32_32x32x16_bf16 v[66:81], v[212:215], v[216:219], v[66:81]
	ds_read_b128 v[212:215], v204 offset:8192
	v_mfma_f32_32x32x16_bf16 v[82:97], v[86:89], v[82:85], 0
	s_waitcnt lgkmcnt(0)
	v_mfma_f32_32x32x16_bf16 v[82:97], v[212:215], v[216:219], v[82:97]
	ds_read_b128 v[212:215], v205
	ds_read_b128 v[216:219], v149
	v_add_u32_e32 v149, s2, v185
	s_waitcnt lgkmcnt(0)
	v_mfma_f32_32x32x16_bf16 v[66:81], v[212:215], v[216:219], v[66:81]
	ds_read_b128 v[212:215], v205 offset:8192
	s_waitcnt lgkmcnt(0)
	v_mfma_f32_32x32x16_bf16 v[82:97], v[212:215], v[216:219], v[82:97]
	ds_read_b128 v[212:215], v206
	ds_read_b128 v[216:219], v149
	v_add_u32_e32 v149, s2, v186
	s_waitcnt lgkmcnt(0)
	v_mfma_f32_32x32x16_bf16 v[66:81], v[212:215], v[216:219], v[66:81]
	ds_read_b128 v[212:215], v206 offset:8192
	s_waitcnt lgkmcnt(0)
	v_mfma_f32_32x32x16_bf16 v[82:97], v[212:215], v[216:219], v[82:97]
	ds_read_b128 v[212:215], v207
	ds_read_b128 v[216:219], v149
	v_add_u32_e32 v149, s2, v187
	s_waitcnt lgkmcnt(0)
	v_mfma_f32_32x32x16_bf16 v[66:81], v[212:215], v[216:219], v[66:81]
	ds_read_b128 v[212:215], v207 offset:8192
	s_waitcnt lgkmcnt(0)
	v_mfma_f32_32x32x16_bf16 v[82:97], v[212:215], v[216:219], v[82:97]
	ds_read_b128 v[212:215], v208
	ds_read_b128 v[216:219], v149
	v_add_u32_e32 v149, s2, v188
	s_waitcnt lgkmcnt(0)
	v_mfma_f32_32x32x16_bf16 v[66:81], v[212:215], v[216:219], v[66:81]
	ds_read_b128 v[212:215], v208 offset:8192
	s_waitcnt lgkmcnt(0)
	v_mfma_f32_32x32x16_bf16 v[82:97], v[212:215], v[216:219], v[82:97]
	ds_read_b128 v[212:215], v209
	ds_read_b128 v[216:219], v149
	v_add_u32_e32 v149, s2, v189
	s_waitcnt lgkmcnt(0)
	v_mfma_f32_32x32x16_bf16 v[66:81], v[212:215], v[216:219], v[66:81]
	ds_read_b128 v[212:215], v209 offset:8192
	s_waitcnt lgkmcnt(0)
	v_mfma_f32_32x32x16_bf16 v[82:97], v[212:215], v[216:219], v[82:97]
	ds_read_b128 v[212:215], v210
	ds_read_b128 v[216:219], v149
	s_waitcnt lgkmcnt(0)
	v_mfma_f32_32x32x16_bf16 v[66:81], v[212:215], v[216:219], v[66:81]
	ds_read_b128 v[212:215], v210 offset:8192
	s_waitcnt lgkmcnt(0)
	v_mfma_f32_32x32x16_bf16 v[82:97], v[212:215], v[216:219], v[82:97]
	s_cbranch_scc1 .LBB0_866
	s_nop 7
	v_mov_b32_e32 v74, 0xf149f2ca
	s_or_b64 vcc, s[4:5], s[22:23]
	v_cndmask_b32_e64 v73, v74, v73, s[84:85]
	v_cndmask_b32_e32 v66, v74, v66, vcc
	v_cndmask_b32_e64 v67, v74, v67, s[4:5]
	v_cndmask_b32_e64 v68, v74, v68, s[80:81]
	v_cndmask_b32_e64 v69, v74, v69, s[78:79]
	v_cndmask_b32_e64 v70, v74, v70, s[76:77]
	v_cndmask_b32_e64 v71, v74, v71, s[90:91]
	v_cndmask_b32_e64 v72, v74, v72, s[88:89]
	v_mov_b32_e32 v75, v74
	v_mov_b32_e32 v76, v74
	v_mov_b32_e32 v77, v74
	v_mov_b32_e32 v78, v74
	v_mov_b32_e32 v79, v74
	v_mov_b32_e32 v80, v74
	v_mov_b32_e32 v81, v74
	v_mov_b32_e32 v82, v74
	v_mov_b32_e32 v83, v74
	v_mov_b32_e32 v84, v74
	v_mov_b32_e32 v85, v74
	v_mov_b32_e32 v86, v74
	v_mov_b32_e32 v87, v74
	v_mov_b32_e32 v88, v74
	v_mov_b32_e32 v89, v74
	v_mov_b32_e32 v90, v74
	v_mov_b32_e32 v91, v74
	v_mov_b32_e32 v92, v74
	v_mov_b32_e32 v93, v74
	v_mov_b32_e32 v94, v74
	v_mov_b32_e32 v95, v74
	v_mov_b32_e32 v96, v74
	v_mov_b32_e32 v97, v74
	s_branch .LBB0_866
